# P2 conv units: each workgroup takes two adjacent units; the second reuses 30 GLU rows from LDS (rows 32..61 -> 0..29) and stages only 32 rows
# speedup vs baseline: 1.0038x; 1.0038x over previous
; #define LAS __attribute__((address_space(3)))
; __device__ __forceinline__ void conv_unit(LAS unsigned char* lds, int u, const bf16* PROJ, const float* conv_w, const float* conv_b, const float* ln_w, const float* ln_b, bf16* MIX, int tid, const WsRef& wsr) {
;     const int lane = tid & 63, wave = tid >> 6;
;     LAS float* U = (LAS float*)lds;
;     const int t0 = (u * 32) % SEQ; const size_t rowb = (size_t)(u * 32 / SEQ) * SEQ;
;     for (int it = tid; it < 62 * 64; it += 512) { const int r = it >> 6, cc = it & 63; const int t = t0 - 15 + r;
;         f32x4 u0 = (f32x4){0.f, 0.f, 0.f, 0.f}, u1 = u0;
;         if (t >= 0 && t < SEQ) { const bf16* pr = PROJ + (rowb + t) * INC + 2048 + cc * 8; const u32x4 a = *(const u32x4*)pr, g = *(const u32x4*)(pr + 512);
; #pragma unroll
;             for (int e = 0; e < 4; ++e) { const float a0 = bflo(a[e]), a1 = bfhi(a[e]), g0 = bflo(g[e]), g1 = bfhi(g[e]);
;                 const float v0 = a0 * __builtin_amdgcn_rcpf(1.f + __expf(-g0)), v1 = a1 * __builtin_amdgcn_rcpf(1.f + __expf(-g1));
;                 if (e < 2) { u0[2 * e] = v0; u0[2 * e + 1] = v1; } else { u1[2 * e - 4] = v0; u1[2 * e - 3] = v1; } } }
;         *(LAS f32x4*)(U + r * 512 + cc * 8) = u0; *(LAS f32x4*)(U + r * 512 + cc * 8 + 4) = u1; }
;     float w[31];
; #pragma unroll
;     for (int k = 0; k < 31; ++k) w[k] = conv_w[k * 512 + tid];
;     const float bias = conv_b[tid];
;     __syncthreads();
;     for (int tb = 0; tb < 4; ++tb) {
;         float uw[38];
; #pragma unroll
;         for (int r = 0; r < 38; ++r) uw[r] = U[(tb * 8 + r) * 512 + tid];
;         typedef float f2v __attribute__((ext_vector_type(2)));
;         f2v y2[4];
; #pragma unroll
;         for (int t = 0; t < 4; ++t) y2[t] = (f2v){bias, bias};
; #pragma unroll
;         for (int k = 0; k < 31; ++k) { const f2v wk = (f2v){w[k], w[k]};
; #pragma unroll
;             for (int t = 0; t < 4; ++t) y2[t] = __builtin_elementwise_fma(wk, (f2v){uw[2 * t + k], uw[2 * t + k + 1]}, y2[t]); }
; #pragma unroll
;         for (int t = 0; t < 4; ++t) { U[(tb * 8 + 2 * t) * 512 + tid] = y2[t].x; U[(tb * 8 + 2 * t + 1) * 512 + tid] = y2[t].y; }
;     }
;     __syncthreads();
; #pragma unroll
;     for (int i = 0; i < 4; ++i) { const int tt = wave * 4 + i;
;         const f32x4 a = *(const LAS f32x4*)(U + tt * 512 + lane * 8), b = *(const LAS f32x4*)(U + tt * 512 + lane * 8 + 4);
.LBB0_219:
	v_mov_b32_e32 v9, 0
	v_lshlrev_b32_e32 v8, 2, v128
	v_lshl_add_u64 v[10:11], s[38:39], 0, v[8:9]
	s_mov_b64 s[8:9], 0x1800
	v_lshl_add_u64 v[14:15], v[10:11], 0, s[8:9]
	s_mov_b64 s[8:9], 0x2000
	s_waitcnt vmcnt(19)
	v_lshl_add_u64 v[16:17], v[10:11], 0, s[8:9]
	s_mov_b64 s[8:9], 0x2800
	v_lshl_add_u64 v[18:19], v[10:11], 0, s[8:9]
	s_mov_b64 s[8:9], 0x3000
	s_waitcnt vmcnt(18)
	v_lshl_add_u64 v[20:21], v[10:11], 0, s[8:9]
	s_mov_b64 s[8:9], 0x3800
	v_lshl_add_u64 v[22:23], v[10:11], 0, s[8:9]
	s_mov_b64 s[8:9], 0x4000
	v_and_b32_e32 v2, 0x1f8, v76
	s_waitcnt vmcnt(17)
	v_lshl_add_u64 v[24:25], v[10:11], 0, s[8:9]
	s_mov_b64 s[8:9], 0x4800
	v_lshl_add_u64 v[72:73], s[40:41], 0, v[8:9]
	v_add_u32_e32 v33, 0, v8
	v_lshlrev_b32_e32 v8, 2, v2
	v_lshl_add_u64 v[26:27], v[10:11], 0, s[8:9]
	s_mov_b64 s[8:9], 0x5000
	v_add_u32_e32 v3, 0, v8
	v_lshl_add_u64 v[76:77], s[42:43], 0, v[8:9]
	v_lshl_add_u64 v[78:79], s[44:45], 0, v[8:9]
	v_mbcnt_lo_u32_b32 v8, -1, 0
	s_waitcnt vmcnt(16)
	v_lshl_add_u64 v[28:29], v[10:11], 0, s[8:9]
	s_mov_b64 s[8:9], 0x5800
	v_mbcnt_hi_u32_b32 v8, -1, v8
	v_lshl_add_u64 v[30:31], v[10:11], 0, s[8:9]
	s_mov_b64 s[8:9], 0x6000
	v_and_b32_e32 v84, 64, v8
	v_lshl_add_u64 v[34:35], v[10:11], 0, s[8:9]
	s_mov_b64 s[8:9], 0x6800
	v_add_u32_e32 v84, 64, v84
	v_xor_b32_e32 v88, 1, v8
	v_lshl_add_u64 v[36:37], v[10:11], 0, s[8:9]
	s_mov_b64 s[8:9], 0x7000
	v_cmp_lt_i32_e32 vcc, v88, v84
	v_lshl_add_u64 v[38:39], v[10:11], 0, s[8:9]
	s_mov_b64 s[8:9], 0x7800
	v_cndmask_b32_e32 v88, v8, v88, vcc
	v_lshl_add_u64 v[40:41], v[10:11], 0, s[8:9]
	s_mov_b64 s[8:9], 0x8000
	v_lshlrev_b32_e32 v141, 2, v88
	v_xor_b32_e32 v88, 2, v8
	v_lshl_add_u64 v[42:43], v[10:11], 0, s[8:9]
	s_mov_b64 s[8:9], 0x8800
	v_cmp_lt_i32_e32 vcc, v88, v84
	v_lshl_add_u64 v[44:45], v[10:11], 0, s[8:9]
	s_mov_b64 s[8:9], 0x9000
	v_cndmask_b32_e32 v88, v8, v88, vcc
	v_lshl_add_u64 v[46:47], v[10:11], 0, s[8:9]
	s_mov_b64 s[8:9], 0x9800
	v_lshlrev_b32_e32 v205, 2, v88
	v_xor_b32_e32 v88, 4, v8
	v_lshl_add_u64 v[48:49], v[10:11], 0, s[8:9]
	s_mov_b64 s[8:9], 0xa000
	v_cmp_lt_i32_e32 vcc, v88, v84
	v_lshl_add_u64 v[50:51], v[10:11], 0, s[8:9]
	s_mov_b64 s[8:9], 0xa800
	v_cndmask_b32_e32 v88, v8, v88, vcc
	v_lshl_add_u64 v[52:53], v[10:11], 0, s[8:9]
	s_mov_b64 s[8:9], 0xb000
	v_lshlrev_b32_e32 v206, 2, v88
	v_xor_b32_e32 v88, 8, v8
	v_lshl_add_u64 v[54:55], v[10:11], 0, s[8:9]
	s_mov_b64 s[8:9], 0xb800
	v_cmp_lt_i32_e32 vcc, v88, v84
	v_lshl_add_u64 v[56:57], v[10:11], 0, s[8:9]
	s_mov_b64 s[8:9], 0xc000
	v_cndmask_b32_e32 v88, v8, v88, vcc
	v_lshl_add_u64 v[58:59], v[10:11], 0, s[8:9]
	s_mov_b64 s[8:9], 0xc800
	v_lshlrev_b32_e32 v207, 2, v88
	v_xor_b32_e32 v88, 16, v8
	v_lshl_add_u64 v[60:61], v[10:11], 0, s[8:9]
	s_mov_b64 s[8:9], 0xd000
	v_cmp_lt_i32_e32 vcc, v88, v84
	v_lshl_add_u64 v[62:63], v[10:11], 0, s[8:9]
	s_mov_b64 s[8:9], 0xd800
	v_cndmask_b32_e32 v88, v8, v88, vcc
	v_lshl_add_u64 v[64:65], v[10:11], 0, s[8:9]
	s_mov_b64 s[8:9], 0xe000
	v_and_b32_e32 v74, 60, v32
	v_lshlrev_b32_e32 v208, 2, v88
	v_xor_b32_e32 v88, 32, v8
	v_lshl_add_u64 v[66:67], v[10:11], 0, s[8:9]
	s_mov_b64 s[8:9], 0xe800
	v_or_b32_e32 v80, 1, v74
	v_or_b32_e32 v82, 2, v74
	v_or_b32_e32 v32, 3, v32
	v_cmp_lt_i32_e32 vcc, v88, v84
	v_lshlrev_b32_e32 v0, 3, v204
	v_lshlrev_b32_e32 v1, 5, v204
	s_mov_b64 s[4:5], 0x1000
	v_lshl_add_u64 v[68:69], v[10:11], 0, s[8:9]
	s_mov_b64 s[8:9], 0xf000
	v_lshlrev_b32_e32 v4, 11, v74
	v_lshlrev_b32_e32 v5, 11, v80
	v_lshlrev_b32_e32 v6, 11, v82
	v_lshlrev_b32_e32 v7, 11, v32
	v_cndmask_b32_e32 v8, v8, v88, vcc
	v_lshl_add_u64 v[12:13], v[10:11], 0, s[4:5]
	v_lshl_add_u64 v[70:71], v[10:11], 0, s[8:9]
	v_add_u32_e32 v81, 0x10000, v33
	v_add_u32_e32 v83, 0x10800, v33
	v_add_u32_e32 v85, 0x11000, v33
	v_add_u32_e32 v87, 0x11800, v33
	v_add_u32_e32 v89, 0x12000, v33
	v_add_u32_e32 v91, 0x12800, v33
	v_add_u32_e32 v93, 0x13000, v33
	v_add_u32_e32 v95, 0x13800, v33
	v_add_u32_e32 v97, 0x14000, v33
	v_add_u32_e32 v99, 0x14800, v33
	v_add_u32_e32 v101, 0x15000, v33
	v_add_u32_e32 v103, 0x15800, v33
	v_add_u32_e32 v105, 0x16000, v33
	v_add_u32_e32 v107, 0x16800, v33
	v_add_u32_e32 v109, 0x17000, v33
	v_add_u32_e32 v111, 0x17800, v33
	v_add_u32_e32 v113, 0x18000, v33
	v_add_u32_e32 v115, 0x18800, v33
	v_add_u32_e32 v117, 0x19000, v33
	v_add_u32_e32 v119, 0x19800, v33
	v_add_u32_e32 v121, 0x1a000, v33
	v_add_u32_e32 v123, 0x1a800, v33
	v_add_u32_e32 v125, 0x1b000, v33
	v_add_u32_e32 v127, 0x1b800, v33
	v_add_u32_e32 v129, 0x1c000, v33
	v_add_u32_e32 v131, 0x1c800, v33
	v_add_u32_e32 v133, 0x1d000, v33
	v_add_u32_e32 v135, 0x1d800, v33
	v_add_u32_e32 v137, 0x1e000, v33
	v_add_u32_e32 v139, 0x1e800, v33
	v_lshlrev_b32_e32 v209, 2, v8
	v_add_u32_e32 v210, 0xfffffe00, v128
	v_add3_u32 v211, v86, v1, 0
	v_add_u32_e32 v75, -15, v75
	s_movk_i32 s24, 0x2000
	s_movk_i32 s25, 0x1800
	v_lshlrev_b32_e32 v8, 1, v0
	s_movk_i32 s26, 0xd7f
	v_add_u32_e32 v212, v3, v4
	v_mov_b32_e32 v213, 0x358637bd
	s_mov_b32 s27, 0x800000
	v_lshlrev_b32_e32 v214, 1, v2
	v_add_u32_e32 v215, v3, v5
	v_add_u32_e32 v216, v3, v6
	v_add_u32_e32 v217, v3, v7
	v_mov_b32_e32 v218, 0x1800
	s_mov_b32 s88, s84
	s_lshl_b32 s28, s2, 1
	s_branch .LBB0_221
; __device__ __forceinline__ void conv_unit(LAS unsigned char* lds, int u, const bf16* PROJ, const float* conv_w, const float* conv_b, const float* ln_w, const float* ln_b, bf16* MIX, int tid, const WsRef& wsr) {
;     ...
;     float w[31];
; #pragma unroll
;     for (int k = 0; k < 31; ++k) w[k] = conv_w[k * 512 + tid];
;     const float bias = conv_b[tid];
;     __syncthreads();
;     for (int tb = 0; tb < 4; ++tb) {
;         float uw[38];
; #pragma unroll
;         for (int r = 0; r < 38; ++r) uw[r] = U[(tb * 8 + r) * 512 + tid];
;         typedef float f2v __attribute__((ext_vector_type(2)));
;         f2v y2[4];
; #pragma unroll
;         for (int t = 0; t < 4; ++t) y2[t] = (f2v){bias, bias};
; #pragma unroll
;         for (int k = 0; k < 31; ++k) { const f2v wk = (f2v){w[k], w[k]};
; #pragma unroll
;             for (int t = 0; t < 4; ++t) y2[t] = __builtin_elementwise_fma(wk, (f2v){uw[2 * t + k], uw[2 * t + k + 1]}, y2[t]); }
; __global__ void __launch_bounds__(512, 2) fwd_mega(Args a) {
;     ...
;         for (int u = bid; u < 512; u += G) conv_unit(lds, u, PROJ, a.in[9], a.in[10], a.in[11], a.in[12], MIX, tid, wsr);
.LBB0_220:
	s_or_b64 exec, exec, s[10:11]
	global_load_dword v138, v[72:73], off
	global_load_dword v140, v[10:11], off
	global_load_dword v136, v[10:11], off offset:2048
	global_load_dword v134, v[12:13], off
	global_load_dword v132, v[14:15], off
	global_load_dword v130, v[16:17], off
	global_load_dword v126, v[18:19], off
	global_load_dword v124, v[20:21], off
	global_load_dword v122, v[22:23], off
	global_load_dword v120, v[24:25], off
	global_load_dword v118, v[26:27], off
	global_load_dword v116, v[28:29], off
	global_load_dword v114, v[30:31], off
	global_load_dword v112, v[34:35], off
	global_load_dword v110, v[36:37], off
	global_load_dword v108, v[38:39], off
	global_load_dword v106, v[40:41], off
	global_load_dword v104, v[42:43], off
	global_load_dword v102, v[44:45], off
	global_load_dword v100, v[46:47], off
	global_load_dword v98, v[48:49], off
	global_load_dword v96, v[50:51], off
	global_load_dword v94, v[52:53], off
	global_load_dword v92, v[54:55], off
	global_load_dword v90, v[56:57], off
	global_load_dword v88, v[58:59], off
	global_load_dword v86, v[60:61], off
	global_load_dword v84, v[62:63], off
	global_load_dword v6, v[64:65], off
	global_load_dword v4, v[66:67], off
	global_load_dword v2, v[68:69], off
	global_load_dword v0, v[70:71], off
	s_waitcnt lgkmcnt(0)
	s_barrier
	ds_read2st64_b32 v[158:159], v33 offset1:8
	ds_read2st64_b32 v[160:161], v33 offset0:16 offset1:24
	ds_read2st64_b32 v[162:163], v33 offset0:32 offset1:40
	ds_read2st64_b32 v[164:165], v33 offset0:48 offset1:56
	ds_read2st64_b32 v[194:195], v33 offset0:64 offset1:72
	ds_read2st64_b32 v[192:193], v33 offset0:80 offset1:88
	ds_read2st64_b32 v[190:191], v33 offset0:96 offset1:104
	ds_read2st64_b32 v[188:189], v33 offset0:112 offset1:120
	ds_read2st64_b32 v[156:157], v33 offset0:128 offset1:136
	ds_read2st64_b32 v[154:155], v33 offset0:144 offset1:152
	ds_read2st64_b32 v[152:153], v33 offset0:160 offset1:168
	ds_read2st64_b32 v[150:151], v33 offset0:176 offset1:184
	ds_read2st64_b32 v[148:149], v33 offset0:192 offset1:200
	ds_read2st64_b32 v[146:147], v33 offset0:208 offset1:216
	ds_read2st64_b32 v[144:145], v33 offset0:224 offset1:232
	ds_read2st64_b32 v[142:143], v33 offset0:240 offset1:248
	s_waitcnt lgkmcnt(14)
	v_mov_b32_e32 v166, v159
	v_mov_b32_e32 v167, v160
	v_mov_b32_e32 v168, v161
	s_waitcnt lgkmcnt(13)
	v_mov_b32_e32 v169, v162
	v_mov_b32_e32 v170, v163
	s_waitcnt lgkmcnt(12)
	v_mov_b32_e32 v171, v164
	v_mov_b32_e32 v172, v165
	s_waitcnt lgkmcnt(11)
	v_mov_b32_e32 v173, v194
	v_mov_b32_e32 v196, v195
	s_waitcnt lgkmcnt(10)
	v_mov_b32_e32 v197, v192
	v_mov_b32_e32 v198, v193
	s_waitcnt lgkmcnt(9)
	v_mov_b32_e32 v199, v190
	v_mov_b32_e32 v200, v191
	s_waitcnt lgkmcnt(8)
	v_mov_b32_e32 v201, v188
	v_mov_b32_e32 v202, v189
	s_waitcnt lgkmcnt(7)
	v_mov_b32_e32 v203, v156
	v_mov_b32_e32 v180, v157
	s_waitcnt lgkmcnt(6)
	v_mov_b32_e32 v181, v154
	v_mov_b32_e32 v182, v155
	s_waitcnt lgkmcnt(5)
	v_mov_b32_e32 v183, v152
	v_mov_b32_e32 v184, v153
	s_waitcnt lgkmcnt(4)
	v_mov_b32_e32 v185, v150
	v_mov_b32_e32 v186, v151
	s_waitcnt lgkmcnt(3)
	v_mov_b32_e32 v187, v148
	s_add_i32 s3, s8, s3
	v_readlane_b32 s8, v255, 8
	s_add_i32 s28, s28, 1
	s_bitcmp1_b32 s28, 0
	v_readlane_b32 s9, v255, 9
	s_waitcnt vmcnt(30)
	v_pk_fma_f32 v[158:159], v[140:141], v[158:159], v[138:139] op_sel_hi:[0,1,0]
	v_pk_fma_f32 v[174:175], v[140:141], v[160:161], v[138:139] op_sel_hi:[0,1,0]
	v_pk_fma_f32 v[176:177], v[140:141], v[162:163], v[138:139] op_sel_hi:[0,1,0]
	v_pk_fma_f32 v[178:179], v[140:141], v[164:165], v[138:139] op_sel_hi:[0,1,0]
	s_waitcnt vmcnt(29)
	v_pk_fma_f32 v[158:159], v[136:137], v[166:167], v[158:159] op_sel_hi:[0,1,1]
	v_pk_fma_f32 v[166:167], v[136:137], v[168:169], v[174:175] op_sel_hi:[0,1,1]
	v_pk_fma_f32 v[174:175], v[136:137], v[170:171], v[176:177] op_sel_hi:[0,1,1]
	v_pk_fma_f32 v[176:177], v[136:137], v[172:173], v[178:179] op_sel_hi:[0,1,1]
	s_waitcnt vmcnt(28)
	v_pk_fma_f32 v[158:159], v[134:135], v[160:161], v[158:159] op_sel_hi:[0,1,1]
	v_pk_fma_f32 v[160:161], v[134:135], v[162:163], v[166:167] op_sel_hi:[0,1,1]
	v_pk_fma_f32 v[166:167], v[134:135], v[164:165], v[174:175] op_sel_hi:[0,1,1]
	v_pk_fma_f32 v[174:175], v[134:135], v[194:195], v[176:177] op_sel_hi:[0,1,1]
	s_waitcnt vmcnt(27)
	v_pk_fma_f32 v[158:159], v[132:133], v[168:169], v[158:159] op_sel_hi:[0,1,1]
	v_pk_fma_f32 v[160:161], v[132:133], v[170:171], v[160:161] op_sel_hi:[0,1,1]
	v_pk_fma_f32 v[166:167], v[132:133], v[172:173], v[166:167] op_sel_hi:[0,1,1]
	v_pk_fma_f32 v[168:169], v[132:133], v[196:197], v[174:175] op_sel_hi:[0,1,1]
	s_waitcnt vmcnt(26)
	v_pk_fma_f32 v[158:159], v[130:131], v[162:163], v[158:159] op_sel_hi:[0,1,1]
	v_pk_fma_f32 v[160:161], v[130:131], v[164:165], v[160:161] op_sel_hi:[0,1,1]
	v_pk_fma_f32 v[162:163], v[130:131], v[194:195], v[166:167] op_sel_hi:[0,1,1]
	v_pk_fma_f32 v[166:167], v[130:131], v[192:193], v[168:169] op_sel_hi:[0,1,1]
	s_waitcnt vmcnt(25)
	v_pk_fma_f32 v[160:161], v[126:127], v[172:173], v[160:161] op_sel_hi:[0,1,1]
	v_pk_fma_f32 v[162:163], v[126:127], v[196:197], v[162:163] op_sel_hi:[0,1,1]
	v_pk_fma_f32 v[158:159], v[126:127], v[170:171], v[158:159] op_sel_hi:[0,1,1]
	v_pk_fma_f32 v[166:167], v[126:127], v[198:199], v[166:167] op_sel_hi:[0,1,1]
	s_waitcnt vmcnt(24)
	v_pk_fma_f32 v[160:161], v[124:125], v[194:195], v[160:161] op_sel_hi:[0,1,1]
	v_pk_fma_f32 v[162:163], v[124:125], v[192:193], v[162:163] op_sel_hi:[0,1,1]
	v_pk_fma_f32 v[158:159], v[124:125], v[164:165], v[158:159] op_sel_hi:[0,1,1]
	v_pk_fma_f32 v[164:165], v[124:125], v[190:191], v[166:167] op_sel_hi:[0,1,1]
	s_waitcnt vmcnt(23)
; __device__ __forceinline__ void conv_unit(LAS unsigned char* lds, int u, const bf16* PROJ, const float* conv_w, const float* conv_b, const float* ln_w, const float* ln_b, bf16* MIX, int tid, const WsRef& wsr) {
;     ...
; #pragma unroll
;         for (int t = 0; t < 4; ++t) y2[t] = (f2v){bias, bias};
; #pragma unroll
;         for (int k = 0; k < 31; ++k) { const f2v wk = (f2v){w[k], w[k]};
; #pragma unroll
;             for (int t = 0; t < 4; ++t) y2[t] = __builtin_elementwise_fma(wk, (f2v){uw[2 * t + k], uw[2 * t + k + 1]}, y2[t]); }
	v_pk_fma_f32 v[160:161], v[122:123], v[196:197], v[160:161] op_sel_hi:[0,1,1]
	v_pk_fma_f32 v[162:163], v[122:123], v[198:199], v[162:163] op_sel_hi:[0,1,1]
	v_pk_fma_f32 v[158:159], v[122:123], v[172:173], v[158:159] op_sel_hi:[0,1,1]
	v_pk_fma_f32 v[164:165], v[122:123], v[200:201], v[164:165] op_sel_hi:[0,1,1]
	s_waitcnt vmcnt(22)
	v_pk_fma_f32 v[160:161], v[120:121], v[192:193], v[160:161] op_sel_hi:[0,1,1]
	v_pk_fma_f32 v[162:163], v[120:121], v[190:191], v[162:163] op_sel_hi:[0,1,1]
	v_pk_fma_f32 v[158:159], v[120:121], v[194:195], v[158:159] op_sel_hi:[0,1,1]
	v_pk_fma_f32 v[164:165], v[120:121], v[188:189], v[164:165] op_sel_hi:[0,1,1]
	s_waitcnt vmcnt(21)
	v_pk_fma_f32 v[160:161], v[118:119], v[198:199], v[160:161] op_sel_hi:[0,1,1]
	v_pk_fma_f32 v[162:163], v[118:119], v[200:201], v[162:163] op_sel_hi:[0,1,1]
	v_pk_fma_f32 v[158:159], v[118:119], v[196:197], v[158:159] op_sel_hi:[0,1,1]
	v_pk_fma_f32 v[164:165], v[118:119], v[202:203], v[164:165] op_sel_hi:[0,1,1]
	s_waitcnt vmcnt(20)
	v_pk_fma_f32 v[160:161], v[116:117], v[190:191], v[160:161] op_sel_hi:[0,1,1]
	v_pk_fma_f32 v[162:163], v[116:117], v[188:189], v[162:163] op_sel_hi:[0,1,1]
	v_pk_fma_f32 v[158:159], v[116:117], v[192:193], v[158:159] op_sel_hi:[0,1,1]
	v_pk_fma_f32 v[164:165], v[116:117], v[156:157], v[164:165] op_sel_hi:[0,1,1]
	s_waitcnt vmcnt(19)
	v_pk_fma_f32 v[160:161], v[114:115], v[200:201], v[160:161] op_sel_hi:[0,1,1]
	v_pk_fma_f32 v[162:163], v[114:115], v[202:203], v[162:163] op_sel_hi:[0,1,1]
	v_pk_fma_f32 v[158:159], v[114:115], v[198:199], v[158:159] op_sel_hi:[0,1,1]
	v_pk_fma_f32 v[164:165], v[114:115], v[180:181], v[164:165] op_sel_hi:[0,1,1]
	s_waitcnt vmcnt(18)
	v_pk_fma_f32 v[160:161], v[112:113], v[188:189], v[160:161] op_sel_hi:[0,1,1]
	v_pk_fma_f32 v[162:163], v[112:113], v[156:157], v[162:163] op_sel_hi:[0,1,1]
	v_pk_fma_f32 v[158:159], v[112:113], v[190:191], v[158:159] op_sel_hi:[0,1,1]
	v_pk_fma_f32 v[164:165], v[112:113], v[154:155], v[164:165] op_sel_hi:[0,1,1]
	s_waitcnt vmcnt(17)
	v_pk_fma_f32 v[160:161], v[110:111], v[202:203], v[160:161] op_sel_hi:[0,1,1]
	v_pk_fma_f32 v[162:163], v[110:111], v[180:181], v[162:163] op_sel_hi:[0,1,1]
	v_pk_fma_f32 v[158:159], v[110:111], v[200:201], v[158:159] op_sel_hi:[0,1,1]
	v_pk_fma_f32 v[164:165], v[110:111], v[182:183], v[164:165] op_sel_hi:[0,1,1]
	s_waitcnt vmcnt(16)
	v_pk_fma_f32 v[160:161], v[108:109], v[156:157], v[160:161] op_sel_hi:[0,1,1]
	v_pk_fma_f32 v[162:163], v[108:109], v[154:155], v[162:163] op_sel_hi:[0,1,1]
	v_pk_fma_f32 v[158:159], v[108:109], v[188:189], v[158:159] op_sel_hi:[0,1,1]
	v_pk_fma_f32 v[164:165], v[108:109], v[152:153], v[164:165] op_sel_hi:[0,1,1]
	s_waitcnt vmcnt(15)
	v_pk_fma_f32 v[160:161], v[106:107], v[180:181], v[160:161] op_sel_hi:[0,1,1]
	v_pk_fma_f32 v[162:163], v[106:107], v[182:183], v[162:163] op_sel_hi:[0,1,1]
	v_pk_fma_f32 v[158:159], v[106:107], v[202:203], v[158:159] op_sel_hi:[0,1,1]
	v_pk_fma_f32 v[164:165], v[106:107], v[184:185], v[164:165] op_sel_hi:[0,1,1]
	s_waitcnt vmcnt(14)
	v_pk_fma_f32 v[160:161], v[104:105], v[154:155], v[160:161] op_sel_hi:[0,1,1]
	v_pk_fma_f32 v[162:163], v[104:105], v[152:153], v[162:163] op_sel_hi:[0,1,1]
	v_pk_fma_f32 v[158:159], v[104:105], v[156:157], v[158:159] op_sel_hi:[0,1,1]
	v_pk_fma_f32 v[164:165], v[104:105], v[150:151], v[164:165] op_sel_hi:[0,1,1]
	s_waitcnt vmcnt(13)
	v_pk_fma_f32 v[160:161], v[102:103], v[182:183], v[160:161] op_sel_hi:[0,1,1]
	v_pk_fma_f32 v[162:163], v[102:103], v[184:185], v[162:163] op_sel_hi:[0,1,1]
	v_pk_fma_f32 v[158:159], v[102:103], v[180:181], v[158:159] op_sel_hi:[0,1,1]
	v_pk_fma_f32 v[164:165], v[102:103], v[186:187], v[164:165] op_sel_hi:[0,1,1]
	s_waitcnt vmcnt(12)
	v_pk_fma_f32 v[160:161], v[100:101], v[152:153], v[160:161] op_sel_hi:[0,1,1]
	v_pk_fma_f32 v[162:163], v[100:101], v[150:151], v[162:163] op_sel_hi:[0,1,1]
	v_pk_fma_f32 v[158:159], v[100:101], v[154:155], v[158:159] op_sel_hi:[0,1,1]
	v_pk_fma_f32 v[164:165], v[100:101], v[148:149], v[164:165] op_sel_hi:[0,1,1]
	s_waitcnt vmcnt(11)
	v_pk_fma_f32 v[160:161], v[98:99], v[184:185], v[160:161] op_sel_hi:[0,1,1]
	v_pk_fma_f32 v[166:167], v[98:99], v[186:187], v[162:163] op_sel_hi:[0,1,1]
	v_mov_b32_e32 v162, v149
	s_waitcnt lgkmcnt(2)
	v_mov_b32_e32 v163, v146
	v_pk_fma_f32 v[158:159], v[98:99], v[182:183], v[158:159] op_sel_hi:[0,1,1]
	v_pk_fma_f32 v[164:165], v[98:99], v[162:163], v[164:165] op_sel_hi:[0,1,1]
	s_waitcnt vmcnt(10)
	v_pk_fma_f32 v[160:161], v[96:97], v[150:151], v[160:161] op_sel_hi:[0,1,1]
	v_pk_fma_f32 v[158:159], v[96:97], v[152:153], v[158:159] op_sel_hi:[0,1,1]
	v_pk_fma_f32 v[166:167], v[96:97], v[148:149], v[166:167] op_sel_hi:[0,1,1]
	v_pk_fma_f32 v[164:165], v[96:97], v[146:147], v[164:165] op_sel_hi:[0,1,1]
	s_waitcnt vmcnt(9)
	v_pk_fma_f32 v[168:169], v[94:95], v[186:187], v[160:161] op_sel_hi:[0,1,1]
	v_mov_b32_e32 v160, v147
	s_waitcnt lgkmcnt(1)
	v_mov_b32_e32 v161, v144
	v_pk_fma_f32 v[158:159], v[94:95], v[184:185], v[158:159] op_sel_hi:[0,1,1]
	v_pk_fma_f32 v[166:167], v[94:95], v[162:163], v[166:167] op_sel_hi:[0,1,1]
	v_pk_fma_f32 v[164:165], v[94:95], v[160:161], v[164:165] op_sel_hi:[0,1,1]
	s_waitcnt vmcnt(8)
	v_pk_fma_f32 v[168:169], v[92:93], v[148:149], v[168:169] op_sel_hi:[0,1,1]
	v_pk_fma_f32 v[158:159], v[92:93], v[150:151], v[158:159] op_sel_hi:[0,1,1]
	v_pk_fma_f32 v[166:167], v[92:93], v[146:147], v[166:167] op_sel_hi:[0,1,1]
	v_pk_fma_f32 v[164:165], v[92:93], v[144:145], v[164:165] op_sel_hi:[0,1,1]
	s_waitcnt vmcnt(7)
	v_pk_fma_f32 v[170:171], v[90:91], v[162:163], v[168:169] op_sel_hi:[0,1,1]
	v_mov_b32_e32 v168, v145
	s_waitcnt lgkmcnt(0)
; __device__ __forceinline__ void conv_unit(LAS unsigned char* lds, int u, const bf16* PROJ, const float* conv_w, const float* conv_b, const float* ln_w, const float* ln_b, bf16* MIX, int tid, const WsRef& wsr) {
;     ...
;     for (int tb = 0; tb < 4; ++tb) {
;         float uw[38];
; #pragma unroll
;         for (int r = 0; r < 38; ++r) uw[r] = U[(tb * 8 + r) * 512 + tid];
;         typedef float f2v __attribute__((ext_vector_type(2)));
;         f2v y2[4];
; #pragma unroll
;         for (int t = 0; t < 4; ++t) y2[t] = (f2v){bias, bias};
; #pragma unroll
;         for (int k = 0; k < 31; ++k) { const f2v wk = (f2v){w[k], w[k]};
; #pragma unroll
;             for (int t = 0; t < 4; ++t) y2[t] = __builtin_elementwise_fma(wk, (f2v){uw[2 * t + k], uw[2 * t + k + 1]}, y2[t]); }
; #pragma unroll
;         for (int t = 0; t < 4; ++t) { U[(tb * 8 + 2 * t) * 512 + tid] = y2[t].x; U[(tb * 8 + 2 * t + 1) * 512 + tid] = y2[t].y; }
;     }
	v_mov_b32_e32 v169, v142
	v_pk_fma_f32 v[158:159], v[90:91], v[186:187], v[158:159] op_sel_hi:[0,1,1]
	v_pk_fma_f32 v[166:167], v[90:91], v[160:161], v[166:167] op_sel_hi:[0,1,1]
	v_pk_fma_f32 v[164:165], v[90:91], v[168:169], v[164:165] op_sel_hi:[0,1,1]
	s_waitcnt vmcnt(6)
	v_pk_fma_f32 v[158:159], v[88:89], v[148:149], v[158:159] op_sel_hi:[0,1,1]
	v_pk_fma_f32 v[170:171], v[88:89], v[146:147], v[170:171] op_sel_hi:[0,1,1]
	v_pk_fma_f32 v[166:167], v[88:89], v[144:145], v[166:167] op_sel_hi:[0,1,1]
	v_pk_fma_f32 v[220:221], v[88:89], v[142:143], v[164:165] op_sel_hi:[0,1,1]
	v_mov_b32_e32 v174, v143
	s_waitcnt vmcnt(5)
	v_pk_fma_f32 v[222:223], v[86:87], v[162:163], v[158:159] op_sel_hi:[0,1,1]
	v_pk_fma_f32 v[224:225], v[86:87], v[160:161], v[170:171] op_sel_hi:[0,1,1]
	v_pk_fma_f32 v[226:227], v[86:87], v[168:169], v[166:167] op_sel_hi:[0,1,1]
	ds_read_b32 v175, v81
	ds_read_b32 v173, v83
	ds_read_b32 v171, v85
	ds_read_b32 v167, v87
	ds_read_b32 v165, v89
	ds_read_b32 v159, v91
	ds_read_b32 v179, v93
	ds_read_b32 v177, v95
	s_waitcnt lgkmcnt(7)
	v_pk_fma_f32 v[220:221], v[86:87], v[174:175], v[220:221] op_sel_hi:[0,1,1]
	v_mov_b32_e32 v172, v175
	s_waitcnt vmcnt(4)
	v_pk_fma_f32 v[222:223], v[84:85], v[146:147], v[222:223] op_sel_hi:[0,1,1]
	v_pk_fma_f32 v[224:225], v[84:85], v[144:145], v[224:225] op_sel_hi:[0,1,1]
	s_waitcnt lgkmcnt(6)
	v_pk_fma_f32 v[220:221], v[84:85], v[172:173], v[220:221] op_sel_hi:[0,1,1]
	v_mov_b32_e32 v170, v173
	v_pk_fma_f32 v[226:227], v[84:85], v[142:143], v[226:227] op_sel_hi:[0,1,1]
	s_waitcnt vmcnt(3)
	v_pk_fma_f32 v[222:223], v[6:7], v[160:161], v[222:223] op_sel_hi:[0,1,1]
	v_pk_fma_f32 v[224:225], v[6:7], v[168:169], v[224:225] op_sel_hi:[0,1,1]
	s_waitcnt lgkmcnt(5)
	v_pk_fma_f32 v[220:221], v[6:7], v[170:171], v[220:221] op_sel_hi:[0,1,1]
	v_mov_b32_e32 v166, v171
	v_pk_fma_f32 v[226:227], v[6:7], v[174:175], v[226:227] op_sel_hi:[0,1,1]
	s_waitcnt vmcnt(2)
	v_pk_fma_f32 v[222:223], v[4:5], v[144:145], v[222:223] op_sel_hi:[0,1,1]
	v_pk_fma_f32 v[224:225], v[4:5], v[142:143], v[224:225] op_sel_hi:[0,1,1]
	s_waitcnt lgkmcnt(4)
	v_pk_fma_f32 v[220:221], v[4:5], v[166:167], v[220:221] op_sel_hi:[0,1,1]
	v_mov_b32_e32 v164, v167
	v_pk_fma_f32 v[226:227], v[4:5], v[172:173], v[226:227] op_sel_hi:[0,1,1]
	s_waitcnt vmcnt(1)
	v_pk_fma_f32 v[222:223], v[2:3], v[168:169], v[222:223] op_sel_hi:[0,1,1]
	v_pk_fma_f32 v[224:225], v[2:3], v[174:175], v[224:225] op_sel_hi:[0,1,1]
	s_waitcnt lgkmcnt(3)
	v_pk_fma_f32 v[220:221], v[2:3], v[164:165], v[220:221] op_sel_hi:[0,1,1]
	v_mov_b32_e32 v158, v165
	v_pk_fma_f32 v[226:227], v[2:3], v[170:171], v[226:227] op_sel_hi:[0,1,1]
	s_waitcnt vmcnt(0)
	v_pk_fma_f32 v[222:223], v[0:1], v[142:143], v[222:223] op_sel_hi:[0,1,1]
	v_pk_fma_f32 v[224:225], v[0:1], v[172:173], v[224:225] op_sel_hi:[0,1,1]
	s_waitcnt lgkmcnt(2)
	v_pk_fma_f32 v[220:221], v[0:1], v[158:159], v[220:221] op_sel_hi:[0,1,1]
	v_pk_fma_f32 v[226:227], v[0:1], v[166:167], v[226:227] op_sel_hi:[0,1,1]
	ds_write2st64_b32 v33, v222, v223 offset1:8
	ds_write2st64_b32 v33, v224, v225 offset0:16 offset1:24
	ds_write2st64_b32 v33, v226, v227 offset0:32 offset1:40
	ds_write2st64_b32 v33, v220, v221 offset0:48 offset1:56
	v_pk_fma_f32 v[194:195], v[140:141], v[194:195], v[138:139] op_sel_hi:[0,1,0]
	v_pk_fma_f32 v[220:221], v[140:141], v[192:193], v[138:139] op_sel_hi:[0,1,0]
	v_pk_fma_f32 v[222:223], v[140:141], v[190:191], v[138:139] op_sel_hi:[0,1,0]
	v_pk_fma_f32 v[224:225], v[140:141], v[188:189], v[138:139] op_sel_hi:[0,1,0]
	v_pk_fma_f32 v[194:195], v[136:137], v[196:197], v[194:195] op_sel_hi:[0,1,1]
	v_pk_fma_f32 v[196:197], v[136:137], v[198:199], v[220:221] op_sel_hi:[0,1,1]
	v_pk_fma_f32 v[220:221], v[136:137], v[200:201], v[222:223] op_sel_hi:[0,1,1]
	v_pk_fma_f32 v[222:223], v[136:137], v[202:203], v[224:225] op_sel_hi:[0,1,1]
	v_pk_fma_f32 v[192:193], v[134:135], v[192:193], v[194:195] op_sel_hi:[0,1,1]
	v_pk_fma_f32 v[194:195], v[134:135], v[190:191], v[196:197] op_sel_hi:[0,1,1]
	v_pk_fma_f32 v[196:197], v[134:135], v[188:189], v[220:221] op_sel_hi:[0,1,1]
	v_pk_fma_f32 v[220:221], v[134:135], v[156:157], v[222:223] op_sel_hi:[0,1,1]
	v_pk_fma_f32 v[192:193], v[132:133], v[198:199], v[192:193] op_sel_hi:[0,1,1]
	v_pk_fma_f32 v[194:195], v[132:133], v[200:201], v[194:195] op_sel_hi:[0,1,1]
	v_pk_fma_f32 v[196:197], v[132:133], v[202:203], v[196:197] op_sel_hi:[0,1,1]
	v_pk_fma_f32 v[198:199], v[132:133], v[180:181], v[220:221] op_sel_hi:[0,1,1]
	v_pk_fma_f32 v[190:191], v[130:131], v[190:191], v[192:193] op_sel_hi:[0,1,1]
	v_pk_fma_f32 v[192:193], v[130:131], v[188:189], v[194:195] op_sel_hi:[0,1,1]
	v_pk_fma_f32 v[194:195], v[130:131], v[156:157], v[196:197] op_sel_hi:[0,1,1]
	v_pk_fma_f32 v[196:197], v[130:131], v[154:155], v[198:199] op_sel_hi:[0,1,1]
	v_pk_fma_f32 v[190:191], v[126:127], v[200:201], v[190:191] op_sel_hi:[0,1,1]
	v_pk_fma_f32 v[192:193], v[126:127], v[202:203], v[192:193] op_sel_hi:[0,1,1]
	v_pk_fma_f32 v[194:195], v[126:127], v[180:181], v[194:195] op_sel_hi:[0,1,1]
	v_pk_fma_f32 v[196:197], v[126:127], v[182:183], v[196:197] op_sel_hi:[0,1,1]
	v_pk_fma_f32 v[188:189], v[124:125], v[188:189], v[190:191] op_sel_hi:[0,1,1]
	v_pk_fma_f32 v[190:191], v[124:125], v[156:157], v[192:193] op_sel_hi:[0,1,1]
	v_pk_fma_f32 v[192:193], v[124:125], v[154:155], v[194:195] op_sel_hi:[0,1,1]
	v_pk_fma_f32 v[194:195], v[124:125], v[152:153], v[196:197] op_sel_hi:[0,1,1]
	v_pk_fma_f32 v[188:189], v[122:123], v[202:203], v[188:189] op_sel_hi:[0,1,1]
	v_pk_fma_f32 v[190:191], v[122:123], v[180:181], v[190:191] op_sel_hi:[0,1,1]
	v_pk_fma_f32 v[192:193], v[122:123], v[182:183], v[192:193] op_sel_hi:[0,1,1]
; __device__ __forceinline__ void conv_unit(LAS unsigned char* lds, int u, const bf16* PROJ, const float* conv_w, const float* conv_b, const float* ln_w, const float* ln_b, bf16* MIX, int tid, const WsRef& wsr) {
;     ...
;         for (int k = 0; k < 31; ++k) { const f2v wk = (f2v){w[k], w[k]};
; #pragma unroll
;             for (int t = 0; t < 4; ++t) y2[t] = __builtin_elementwise_fma(wk, (f2v){uw[2 * t + k], uw[2 * t + k + 1]}, y2[t]); }
	v_pk_fma_f32 v[194:195], v[122:123], v[184:185], v[194:195] op_sel_hi:[0,1,1]
	v_pk_fma_f32 v[188:189], v[120:121], v[156:157], v[188:189] op_sel_hi:[0,1,1]
	v_pk_fma_f32 v[190:191], v[120:121], v[154:155], v[190:191] op_sel_hi:[0,1,1]
	v_pk_fma_f32 v[192:193], v[120:121], v[152:153], v[192:193] op_sel_hi:[0,1,1]
	v_pk_fma_f32 v[194:195], v[120:121], v[150:151], v[194:195] op_sel_hi:[0,1,1]
	v_pk_fma_f32 v[188:189], v[118:119], v[180:181], v[188:189] op_sel_hi:[0,1,1]
	v_pk_fma_f32 v[190:191], v[118:119], v[182:183], v[190:191] op_sel_hi:[0,1,1]
	v_pk_fma_f32 v[192:193], v[118:119], v[184:185], v[192:193] op_sel_hi:[0,1,1]
	v_pk_fma_f32 v[194:195], v[118:119], v[186:187], v[194:195] op_sel_hi:[0,1,1]
	v_pk_fma_f32 v[188:189], v[116:117], v[154:155], v[188:189] op_sel_hi:[0,1,1]
	v_pk_fma_f32 v[190:191], v[116:117], v[152:153], v[190:191] op_sel_hi:[0,1,1]
	v_pk_fma_f32 v[192:193], v[116:117], v[150:151], v[192:193] op_sel_hi:[0,1,1]
	v_pk_fma_f32 v[194:195], v[116:117], v[148:149], v[194:195] op_sel_hi:[0,1,1]
	v_pk_fma_f32 v[188:189], v[114:115], v[182:183], v[188:189] op_sel_hi:[0,1,1]
	v_pk_fma_f32 v[190:191], v[114:115], v[184:185], v[190:191] op_sel_hi:[0,1,1]
	v_pk_fma_f32 v[192:193], v[114:115], v[186:187], v[192:193] op_sel_hi:[0,1,1]
	v_pk_fma_f32 v[194:195], v[114:115], v[162:163], v[194:195] op_sel_hi:[0,1,1]
	v_pk_fma_f32 v[188:189], v[112:113], v[152:153], v[188:189] op_sel_hi:[0,1,1]
	v_pk_fma_f32 v[190:191], v[112:113], v[150:151], v[190:191] op_sel_hi:[0,1,1]
	v_pk_fma_f32 v[192:193], v[112:113], v[148:149], v[192:193] op_sel_hi:[0,1,1]
	v_pk_fma_f32 v[194:195], v[112:113], v[146:147], v[194:195] op_sel_hi:[0,1,1]
	v_pk_fma_f32 v[188:189], v[110:111], v[184:185], v[188:189] op_sel_hi:[0,1,1]
	v_pk_fma_f32 v[190:191], v[110:111], v[186:187], v[190:191] op_sel_hi:[0,1,1]
	v_pk_fma_f32 v[192:193], v[110:111], v[162:163], v[192:193] op_sel_hi:[0,1,1]
	v_pk_fma_f32 v[194:195], v[110:111], v[160:161], v[194:195] op_sel_hi:[0,1,1]
	v_pk_fma_f32 v[188:189], v[108:109], v[150:151], v[188:189] op_sel_hi:[0,1,1]
	v_pk_fma_f32 v[190:191], v[108:109], v[148:149], v[190:191] op_sel_hi:[0,1,1]
	v_pk_fma_f32 v[192:193], v[108:109], v[146:147], v[192:193] op_sel_hi:[0,1,1]
	v_pk_fma_f32 v[194:195], v[108:109], v[144:145], v[194:195] op_sel_hi:[0,1,1]
	v_pk_fma_f32 v[188:189], v[106:107], v[186:187], v[188:189] op_sel_hi:[0,1,1]
	v_pk_fma_f32 v[190:191], v[106:107], v[162:163], v[190:191] op_sel_hi:[0,1,1]
	v_pk_fma_f32 v[192:193], v[106:107], v[160:161], v[192:193] op_sel_hi:[0,1,1]
	v_pk_fma_f32 v[194:195], v[106:107], v[168:169], v[194:195] op_sel_hi:[0,1,1]
	v_pk_fma_f32 v[188:189], v[104:105], v[148:149], v[188:189] op_sel_hi:[0,1,1]
	v_pk_fma_f32 v[190:191], v[104:105], v[146:147], v[190:191] op_sel_hi:[0,1,1]
	v_pk_fma_f32 v[192:193], v[104:105], v[144:145], v[192:193] op_sel_hi:[0,1,1]
	v_pk_fma_f32 v[194:195], v[104:105], v[142:143], v[194:195] op_sel_hi:[0,1,1]
	v_pk_fma_f32 v[188:189], v[102:103], v[162:163], v[188:189] op_sel_hi:[0,1,1]
	v_pk_fma_f32 v[190:191], v[102:103], v[160:161], v[190:191] op_sel_hi:[0,1,1]
	v_pk_fma_f32 v[192:193], v[102:103], v[168:169], v[192:193] op_sel_hi:[0,1,1]
	v_pk_fma_f32 v[194:195], v[102:103], v[174:175], v[194:195] op_sel_hi:[0,1,1]
	v_pk_fma_f32 v[188:189], v[100:101], v[146:147], v[188:189] op_sel_hi:[0,1,1]
	v_pk_fma_f32 v[190:191], v[100:101], v[144:145], v[190:191] op_sel_hi:[0,1,1]
	v_pk_fma_f32 v[192:193], v[100:101], v[142:143], v[192:193] op_sel_hi:[0,1,1]
	v_pk_fma_f32 v[194:195], v[100:101], v[172:173], v[194:195] op_sel_hi:[0,1,1]
	v_pk_fma_f32 v[188:189], v[98:99], v[160:161], v[188:189] op_sel_hi:[0,1,1]
	v_pk_fma_f32 v[190:191], v[98:99], v[168:169], v[190:191] op_sel_hi:[0,1,1]
	v_pk_fma_f32 v[192:193], v[98:99], v[174:175], v[192:193] op_sel_hi:[0,1,1]
	v_pk_fma_f32 v[194:195], v[98:99], v[170:171], v[194:195] op_sel_hi:[0,1,1]
	v_pk_fma_f32 v[188:189], v[96:97], v[144:145], v[188:189] op_sel_hi:[0,1,1]
	v_pk_fma_f32 v[190:191], v[96:97], v[142:143], v[190:191] op_sel_hi:[0,1,1]
	v_pk_fma_f32 v[192:193], v[96:97], v[172:173], v[192:193] op_sel_hi:[0,1,1]
	v_pk_fma_f32 v[194:195], v[96:97], v[166:167], v[194:195] op_sel_hi:[0,1,1]
	v_pk_fma_f32 v[188:189], v[94:95], v[168:169], v[188:189] op_sel_hi:[0,1,1]
	v_pk_fma_f32 v[190:191], v[94:95], v[174:175], v[190:191] op_sel_hi:[0,1,1]
	v_pk_fma_f32 v[192:193], v[94:95], v[170:171], v[192:193] op_sel_hi:[0,1,1]
	v_pk_fma_f32 v[194:195], v[94:95], v[164:165], v[194:195] op_sel_hi:[0,1,1]
	v_pk_fma_f32 v[188:189], v[92:93], v[142:143], v[188:189] op_sel_hi:[0,1,1]
	v_pk_fma_f32 v[190:191], v[92:93], v[172:173], v[190:191] op_sel_hi:[0,1,1]
	v_pk_fma_f32 v[192:193], v[92:93], v[166:167], v[192:193] op_sel_hi:[0,1,1]
	v_pk_fma_f32 v[194:195], v[92:93], v[158:159], v[194:195] op_sel_hi:[0,1,1]
	v_mov_b32_e32 v178, v159
	v_pk_fma_f32 v[188:189], v[90:91], v[174:175], v[188:189] op_sel_hi:[0,1,1]
	v_pk_fma_f32 v[190:191], v[90:91], v[170:171], v[190:191] op_sel_hi:[0,1,1]
	v_pk_fma_f32 v[192:193], v[90:91], v[164:165], v[192:193] op_sel_hi:[0,1,1]
	s_waitcnt lgkmcnt(5)
	v_pk_fma_f32 v[194:195], v[90:91], v[178:179], v[194:195] op_sel_hi:[0,1,1]
	v_mov_b32_e32 v176, v179
	v_pk_fma_f32 v[188:189], v[88:89], v[172:173], v[188:189] op_sel_hi:[0,1,1]
	v_pk_fma_f32 v[190:191], v[88:89], v[166:167], v[190:191] op_sel_hi:[0,1,1]
	v_pk_fma_f32 v[192:193], v[88:89], v[158:159], v[192:193] op_sel_hi:[0,1,1]
	s_waitcnt lgkmcnt(4)
; __device__ __forceinline__ void conv_unit(LAS unsigned char* lds, int u, const bf16* PROJ, const float* conv_w, const float* conv_b, const float* ln_w, const float* ln_b, bf16* MIX, int tid, const WsRef& wsr) {
;     ...
;         for (int k = 0; k < 31; ++k) { const f2v wk = (f2v){w[k], w[k]};
; #pragma unroll
;             for (int t = 0; t < 4; ++t) y2[t] = __builtin_elementwise_fma(wk, (f2v){uw[2 * t + k], uw[2 * t + k + 1]}, y2[t]); }
; #pragma unroll
;         for (int t = 0; t < 4; ++t) { U[(tb * 8 + 2 * t) * 512 + tid] = y2[t].x; U[(tb * 8 + 2 * t + 1) * 512 + tid] = y2[t].y; }
;     }
	v_pk_fma_f32 v[220:221], v[88:89], v[176:177], v[194:195] op_sel_hi:[0,1,1]
	v_mov_b32_e32 v198, v177
	v_pk_fma_f32 v[222:223], v[86:87], v[170:171], v[188:189] op_sel_hi:[0,1,1]
	v_pk_fma_f32 v[224:225], v[86:87], v[164:165], v[190:191] op_sel_hi:[0,1,1]
	v_pk_fma_f32 v[226:227], v[86:87], v[178:179], v[192:193] op_sel_hi:[0,1,1]
	ds_read_b32 v199, v97
	ds_read_b32 v197, v99
	ds_read_b32 v195, v101
	ds_read_b32 v193, v103
	ds_read_b32 v191, v105
	ds_read_b32 v189, v107
	ds_read_b32 v203, v109
	ds_read_b32 v201, v111
	s_waitcnt lgkmcnt(7)
	v_pk_fma_f32 v[220:221], v[86:87], v[198:199], v[220:221] op_sel_hi:[0,1,1]
	v_mov_b32_e32 v196, v199
	v_pk_fma_f32 v[222:223], v[84:85], v[166:167], v[222:223] op_sel_hi:[0,1,1]
	s_waitcnt lgkmcnt(6)
	v_pk_fma_f32 v[220:221], v[84:85], v[196:197], v[220:221] op_sel_hi:[0,1,1]
	v_mov_b32_e32 v194, v197
	v_pk_fma_f32 v[224:225], v[84:85], v[158:159], v[224:225] op_sel_hi:[0,1,1]
	v_pk_fma_f32 v[226:227], v[84:85], v[176:177], v[226:227] op_sel_hi:[0,1,1]
	v_pk_fma_f32 v[222:223], v[6:7], v[164:165], v[222:223] op_sel_hi:[0,1,1]
	s_waitcnt lgkmcnt(5)
	v_pk_fma_f32 v[220:221], v[6:7], v[194:195], v[220:221] op_sel_hi:[0,1,1]
	v_mov_b32_e32 v192, v195
	v_pk_fma_f32 v[224:225], v[6:7], v[178:179], v[224:225] op_sel_hi:[0,1,1]
	v_pk_fma_f32 v[226:227], v[6:7], v[198:199], v[226:227] op_sel_hi:[0,1,1]
	v_pk_fma_f32 v[222:223], v[4:5], v[158:159], v[222:223] op_sel_hi:[0,1,1]
	s_waitcnt lgkmcnt(4)
	v_pk_fma_f32 v[220:221], v[4:5], v[192:193], v[220:221] op_sel_hi:[0,1,1]
	v_mov_b32_e32 v190, v193
	v_pk_fma_f32 v[224:225], v[4:5], v[176:177], v[224:225] op_sel_hi:[0,1,1]
	v_pk_fma_f32 v[226:227], v[4:5], v[196:197], v[226:227] op_sel_hi:[0,1,1]
	v_pk_fma_f32 v[222:223], v[2:3], v[178:179], v[222:223] op_sel_hi:[0,1,1]
	s_waitcnt lgkmcnt(3)
	v_pk_fma_f32 v[220:221], v[2:3], v[190:191], v[220:221] op_sel_hi:[0,1,1]
	v_mov_b32_e32 v188, v191
	v_pk_fma_f32 v[224:225], v[2:3], v[198:199], v[224:225] op_sel_hi:[0,1,1]
	v_pk_fma_f32 v[226:227], v[2:3], v[194:195], v[226:227] op_sel_hi:[0,1,1]
	v_pk_fma_f32 v[222:223], v[0:1], v[176:177], v[222:223] op_sel_hi:[0,1,1]
	s_waitcnt lgkmcnt(2)
	v_pk_fma_f32 v[220:221], v[0:1], v[188:189], v[220:221] op_sel_hi:[0,1,1]
	v_pk_fma_f32 v[224:225], v[0:1], v[196:197], v[224:225] op_sel_hi:[0,1,1]
	v_pk_fma_f32 v[226:227], v[0:1], v[192:193], v[226:227] op_sel_hi:[0,1,1]
	ds_write2st64_b32 v33, v222, v223 offset0:64 offset1:72
	ds_write2st64_b32 v33, v224, v225 offset0:80 offset1:88
	ds_write2st64_b32 v33, v226, v227 offset0:96 offset1:104
	ds_write2st64_b32 v33, v220, v221 offset0:112 offset1:120
	v_pk_fma_f32 v[156:157], v[140:141], v[156:157], v[138:139] op_sel_hi:[0,1,0]
	v_pk_fma_f32 v[220:221], v[140:141], v[154:155], v[138:139] op_sel_hi:[0,1,0]
	v_pk_fma_f32 v[222:223], v[140:141], v[152:153], v[138:139] op_sel_hi:[0,1,0]
	v_pk_fma_f32 v[224:225], v[140:141], v[150:151], v[138:139] op_sel_hi:[0,1,0]
	v_pk_fma_f32 v[156:157], v[136:137], v[180:181], v[156:157] op_sel_hi:[0,1,1]
	v_pk_fma_f32 v[180:181], v[136:137], v[182:183], v[220:221] op_sel_hi:[0,1,1]
	v_pk_fma_f32 v[220:221], v[136:137], v[184:185], v[222:223] op_sel_hi:[0,1,1]
	v_pk_fma_f32 v[222:223], v[136:137], v[186:187], v[224:225] op_sel_hi:[0,1,1]
	v_pk_fma_f32 v[154:155], v[134:135], v[154:155], v[156:157] op_sel_hi:[0,1,1]
	v_pk_fma_f32 v[156:157], v[134:135], v[152:153], v[180:181] op_sel_hi:[0,1,1]
	v_pk_fma_f32 v[180:181], v[134:135], v[150:151], v[220:221] op_sel_hi:[0,1,1]
	v_pk_fma_f32 v[220:221], v[134:135], v[148:149], v[222:223] op_sel_hi:[0,1,1]
	v_pk_fma_f32 v[154:155], v[132:133], v[182:183], v[154:155] op_sel_hi:[0,1,1]
	v_pk_fma_f32 v[156:157], v[132:133], v[184:185], v[156:157] op_sel_hi:[0,1,1]
	v_pk_fma_f32 v[180:181], v[132:133], v[186:187], v[180:181] op_sel_hi:[0,1,1]
	v_pk_fma_f32 v[182:183], v[132:133], v[162:163], v[220:221] op_sel_hi:[0,1,1]
	v_pk_fma_f32 v[152:153], v[130:131], v[152:153], v[154:155] op_sel_hi:[0,1,1]
	v_pk_fma_f32 v[154:155], v[130:131], v[150:151], v[156:157] op_sel_hi:[0,1,1]
	v_pk_fma_f32 v[156:157], v[130:131], v[148:149], v[180:181] op_sel_hi:[0,1,1]
	v_pk_fma_f32 v[180:181], v[130:131], v[146:147], v[182:183] op_sel_hi:[0,1,1]
	v_pk_fma_f32 v[152:153], v[126:127], v[184:185], v[152:153] op_sel_hi:[0,1,1]
	v_pk_fma_f32 v[154:155], v[126:127], v[186:187], v[154:155] op_sel_hi:[0,1,1]
	v_pk_fma_f32 v[156:157], v[126:127], v[162:163], v[156:157] op_sel_hi:[0,1,1]
	v_pk_fma_f32 v[180:181], v[126:127], v[160:161], v[180:181] op_sel_hi:[0,1,1]
	v_pk_fma_f32 v[150:151], v[124:125], v[150:151], v[152:153] op_sel_hi:[0,1,1]
	v_pk_fma_f32 v[152:153], v[124:125], v[148:149], v[154:155] op_sel_hi:[0,1,1]
	v_pk_fma_f32 v[154:155], v[124:125], v[146:147], v[156:157] op_sel_hi:[0,1,1]
	v_pk_fma_f32 v[156:157], v[124:125], v[144:145], v[180:181] op_sel_hi:[0,1,1]
	v_pk_fma_f32 v[150:151], v[122:123], v[186:187], v[150:151] op_sel_hi:[0,1,1]
	v_pk_fma_f32 v[152:153], v[122:123], v[162:163], v[152:153] op_sel_hi:[0,1,1]
	v_pk_fma_f32 v[154:155], v[122:123], v[160:161], v[154:155] op_sel_hi:[0,1,1]
	v_pk_fma_f32 v[156:157], v[122:123], v[168:169], v[156:157] op_sel_hi:[0,1,1]
	v_pk_fma_f32 v[150:151], v[120:121], v[148:149], v[150:151] op_sel_hi:[0,1,1]
	v_pk_fma_f32 v[152:153], v[120:121], v[146:147], v[152:153] op_sel_hi:[0,1,1]
	v_pk_fma_f32 v[154:155], v[120:121], v[144:145], v[154:155] op_sel_hi:[0,1,1]
	v_pk_fma_f32 v[156:157], v[120:121], v[142:143], v[156:157] op_sel_hi:[0,1,1]
	v_pk_fma_f32 v[150:151], v[118:119], v[162:163], v[150:151] op_sel_hi:[0,1,1]
	v_pk_fma_f32 v[152:153], v[118:119], v[160:161], v[152:153] op_sel_hi:[0,1,1]
; __device__ __forceinline__ void conv_unit(LAS unsigned char* lds, int u, const bf16* PROJ, const float* conv_w, const float* conv_b, const float* ln_w, const float* ln_b, bf16* MIX, int tid, const WsRef& wsr) {
;     ...
;         for (int k = 0; k < 31; ++k) { const f2v wk = (f2v){w[k], w[k]};
; #pragma unroll
;             for (int t = 0; t < 4; ++t) y2[t] = __builtin_elementwise_fma(wk, (f2v){uw[2 * t + k], uw[2 * t + k + 1]}, y2[t]); }
	v_pk_fma_f32 v[154:155], v[118:119], v[168:169], v[154:155] op_sel_hi:[0,1,1]
	v_pk_fma_f32 v[156:157], v[118:119], v[174:175], v[156:157] op_sel_hi:[0,1,1]
	v_pk_fma_f32 v[150:151], v[116:117], v[146:147], v[150:151] op_sel_hi:[0,1,1]
	v_pk_fma_f32 v[152:153], v[116:117], v[144:145], v[152:153] op_sel_hi:[0,1,1]
	v_pk_fma_f32 v[154:155], v[116:117], v[142:143], v[154:155] op_sel_hi:[0,1,1]
	v_pk_fma_f32 v[156:157], v[116:117], v[172:173], v[156:157] op_sel_hi:[0,1,1]
	v_pk_fma_f32 v[150:151], v[114:115], v[160:161], v[150:151] op_sel_hi:[0,1,1]
	v_pk_fma_f32 v[152:153], v[114:115], v[168:169], v[152:153] op_sel_hi:[0,1,1]
	v_pk_fma_f32 v[154:155], v[114:115], v[174:175], v[154:155] op_sel_hi:[0,1,1]
	v_pk_fma_f32 v[156:157], v[114:115], v[170:171], v[156:157] op_sel_hi:[0,1,1]
	v_pk_fma_f32 v[150:151], v[112:113], v[144:145], v[150:151] op_sel_hi:[0,1,1]
	v_pk_fma_f32 v[152:153], v[112:113], v[142:143], v[152:153] op_sel_hi:[0,1,1]
	v_pk_fma_f32 v[154:155], v[112:113], v[172:173], v[154:155] op_sel_hi:[0,1,1]
	v_pk_fma_f32 v[156:157], v[112:113], v[166:167], v[156:157] op_sel_hi:[0,1,1]
	v_pk_fma_f32 v[150:151], v[110:111], v[168:169], v[150:151] op_sel_hi:[0,1,1]
	v_pk_fma_f32 v[152:153], v[110:111], v[174:175], v[152:153] op_sel_hi:[0,1,1]
	v_pk_fma_f32 v[154:155], v[110:111], v[170:171], v[154:155] op_sel_hi:[0,1,1]
	v_pk_fma_f32 v[156:157], v[110:111], v[164:165], v[156:157] op_sel_hi:[0,1,1]
	v_pk_fma_f32 v[150:151], v[108:109], v[142:143], v[150:151] op_sel_hi:[0,1,1]
	v_pk_fma_f32 v[152:153], v[108:109], v[172:173], v[152:153] op_sel_hi:[0,1,1]
	v_pk_fma_f32 v[154:155], v[108:109], v[166:167], v[154:155] op_sel_hi:[0,1,1]
	v_pk_fma_f32 v[156:157], v[108:109], v[158:159], v[156:157] op_sel_hi:[0,1,1]
	v_pk_fma_f32 v[150:151], v[106:107], v[174:175], v[150:151] op_sel_hi:[0,1,1]
	v_pk_fma_f32 v[152:153], v[106:107], v[170:171], v[152:153] op_sel_hi:[0,1,1]
	v_pk_fma_f32 v[154:155], v[106:107], v[164:165], v[154:155] op_sel_hi:[0,1,1]
	v_pk_fma_f32 v[156:157], v[106:107], v[178:179], v[156:157] op_sel_hi:[0,1,1]
	v_pk_fma_f32 v[150:151], v[104:105], v[172:173], v[150:151] op_sel_hi:[0,1,1]
	v_pk_fma_f32 v[152:153], v[104:105], v[166:167], v[152:153] op_sel_hi:[0,1,1]
	v_pk_fma_f32 v[154:155], v[104:105], v[158:159], v[154:155] op_sel_hi:[0,1,1]
	v_pk_fma_f32 v[156:157], v[104:105], v[176:177], v[156:157] op_sel_hi:[0,1,1]
	v_pk_fma_f32 v[150:151], v[102:103], v[170:171], v[150:151] op_sel_hi:[0,1,1]
	v_pk_fma_f32 v[152:153], v[102:103], v[164:165], v[152:153] op_sel_hi:[0,1,1]
	v_pk_fma_f32 v[154:155], v[102:103], v[178:179], v[154:155] op_sel_hi:[0,1,1]
	v_pk_fma_f32 v[156:157], v[102:103], v[198:199], v[156:157] op_sel_hi:[0,1,1]
	v_pk_fma_f32 v[150:151], v[100:101], v[166:167], v[150:151] op_sel_hi:[0,1,1]
	v_pk_fma_f32 v[152:153], v[100:101], v[158:159], v[152:153] op_sel_hi:[0,1,1]
	v_pk_fma_f32 v[154:155], v[100:101], v[176:177], v[154:155] op_sel_hi:[0,1,1]
	v_pk_fma_f32 v[156:157], v[100:101], v[196:197], v[156:157] op_sel_hi:[0,1,1]
	v_pk_fma_f32 v[150:151], v[98:99], v[164:165], v[150:151] op_sel_hi:[0,1,1]
	v_pk_fma_f32 v[152:153], v[98:99], v[178:179], v[152:153] op_sel_hi:[0,1,1]
	v_pk_fma_f32 v[154:155], v[98:99], v[198:199], v[154:155] op_sel_hi:[0,1,1]
	v_pk_fma_f32 v[156:157], v[98:99], v[194:195], v[156:157] op_sel_hi:[0,1,1]
	v_pk_fma_f32 v[150:151], v[96:97], v[158:159], v[150:151] op_sel_hi:[0,1,1]
	v_pk_fma_f32 v[152:153], v[96:97], v[176:177], v[152:153] op_sel_hi:[0,1,1]
	v_pk_fma_f32 v[154:155], v[96:97], v[196:197], v[154:155] op_sel_hi:[0,1,1]
	v_pk_fma_f32 v[156:157], v[96:97], v[192:193], v[156:157] op_sel_hi:[0,1,1]
	v_pk_fma_f32 v[150:151], v[94:95], v[178:179], v[150:151] op_sel_hi:[0,1,1]
	v_pk_fma_f32 v[152:153], v[94:95], v[198:199], v[152:153] op_sel_hi:[0,1,1]
	v_pk_fma_f32 v[154:155], v[94:95], v[194:195], v[154:155] op_sel_hi:[0,1,1]
	v_pk_fma_f32 v[156:157], v[94:95], v[190:191], v[156:157] op_sel_hi:[0,1,1]
	v_pk_fma_f32 v[150:151], v[92:93], v[176:177], v[150:151] op_sel_hi:[0,1,1]
	v_pk_fma_f32 v[152:153], v[92:93], v[196:197], v[152:153] op_sel_hi:[0,1,1]
	v_pk_fma_f32 v[154:155], v[92:93], v[192:193], v[154:155] op_sel_hi:[0,1,1]
	v_pk_fma_f32 v[156:157], v[92:93], v[188:189], v[156:157] op_sel_hi:[0,1,1]
	v_pk_fma_f32 v[150:151], v[90:91], v[198:199], v[150:151] op_sel_hi:[0,1,1]
	v_pk_fma_f32 v[152:153], v[90:91], v[194:195], v[152:153] op_sel_hi:[0,1,1]
	v_pk_fma_f32 v[154:155], v[90:91], v[190:191], v[154:155] op_sel_hi:[0,1,1]
	v_mov_b32_e32 v202, v189
	s_waitcnt lgkmcnt(5)
	v_pk_fma_f32 v[156:157], v[90:91], v[202:203], v[156:157] op_sel_hi:[0,1,1]
	v_pk_fma_f32 v[150:151], v[88:89], v[196:197], v[150:151] op_sel_hi:[0,1,1]
	v_pk_fma_f32 v[152:153], v[88:89], v[192:193], v[152:153] op_sel_hi:[0,1,1]
	v_pk_fma_f32 v[154:155], v[88:89], v[188:189], v[154:155] op_sel_hi:[0,1,1]
	v_mov_b32_e32 v200, v203
	s_waitcnt lgkmcnt(4)
	v_pk_fma_f32 v[156:157], v[88:89], v[200:201], v[156:157] op_sel_hi:[0,1,1]
	v_pk_fma_f32 v[150:151], v[86:87], v[194:195], v[150:151] op_sel_hi:[0,1,1]
	v_pk_fma_f32 v[152:153], v[86:87], v[190:191], v[152:153] op_sel_hi:[0,1,1]
	v_pk_fma_f32 v[154:155], v[86:87], v[202:203], v[154:155] op_sel_hi:[0,1,1]
	v_mov_b32_e32 v180, v201
	ds_read_b32 v181, v113
	ds_read_b32 v183, v115
	ds_read_b32 v185, v117
	ds_read_b32 v187, v119
	ds_read_b32 v221, v121
	ds_read_b32 v223, v123
	ds_read_b32 v225, v125
	ds_read_b32 v227, v127
	s_waitcnt lgkmcnt(7)
	v_pk_fma_f32 v[156:157], v[86:87], v[180:181], v[156:157] op_sel_hi:[0,1,1]
	v_pk_fma_f32 v[150:151], v[84:85], v[192:193], v[150:151] op_sel_hi:[0,1,1]
	v_pk_fma_f32 v[152:153], v[84:85], v[188:189], v[152:153] op_sel_hi:[0,1,1]
	v_pk_fma_f32 v[154:155], v[84:85], v[200:201], v[154:155] op_sel_hi:[0,1,1]
	v_mov_b32_e32 v182, v181
	s_waitcnt lgkmcnt(6)
; __device__ __forceinline__ void conv_unit(LAS unsigned char* lds, int u, const bf16* PROJ, const float* conv_w, const float* conv_b, const float* ln_w, const float* ln_b, bf16* MIX, int tid, const WsRef& wsr) {
;     ...
;         for (int k = 0; k < 31; ++k) { const f2v wk = (f2v){w[k], w[k]};
; #pragma unroll
;             for (int t = 0; t < 4; ++t) y2[t] = __builtin_elementwise_fma(wk, (f2v){uw[2 * t + k], uw[2 * t + k + 1]}, y2[t]); }
; #pragma unroll
;         for (int t = 0; t < 4; ++t) { U[(tb * 8 + 2 * t) * 512 + tid] = y2[t].x; U[(tb * 8 + 2 * t + 1) * 512 + tid] = y2[t].y; }
;     }
	v_pk_fma_f32 v[156:157], v[84:85], v[182:183], v[156:157] op_sel_hi:[0,1,1]
	v_pk_fma_f32 v[150:151], v[6:7], v[190:191], v[150:151] op_sel_hi:[0,1,1]
	v_pk_fma_f32 v[152:153], v[6:7], v[202:203], v[152:153] op_sel_hi:[0,1,1]
	v_pk_fma_f32 v[154:155], v[6:7], v[180:181], v[154:155] op_sel_hi:[0,1,1]
	v_mov_b32_e32 v184, v183
	s_waitcnt lgkmcnt(5)
	v_pk_fma_f32 v[156:157], v[6:7], v[184:185], v[156:157] op_sel_hi:[0,1,1]
	v_pk_fma_f32 v[150:151], v[4:5], v[188:189], v[150:151] op_sel_hi:[0,1,1]
	v_pk_fma_f32 v[152:153], v[4:5], v[200:201], v[152:153] op_sel_hi:[0,1,1]
	v_pk_fma_f32 v[154:155], v[4:5], v[182:183], v[154:155] op_sel_hi:[0,1,1]
	v_mov_b32_e32 v186, v185
	s_waitcnt lgkmcnt(4)
	v_pk_fma_f32 v[156:157], v[4:5], v[186:187], v[156:157] op_sel_hi:[0,1,1]
	v_pk_fma_f32 v[150:151], v[2:3], v[202:203], v[150:151] op_sel_hi:[0,1,1]
	v_pk_fma_f32 v[152:153], v[2:3], v[180:181], v[152:153] op_sel_hi:[0,1,1]
	v_pk_fma_f32 v[154:155], v[2:3], v[184:185], v[154:155] op_sel_hi:[0,1,1]
	v_mov_b32_e32 v220, v187
	s_waitcnt lgkmcnt(3)
	v_pk_fma_f32 v[156:157], v[2:3], v[220:221], v[156:157] op_sel_hi:[0,1,1]
	v_pk_fma_f32 v[150:151], v[0:1], v[200:201], v[150:151] op_sel_hi:[0,1,1]
	v_pk_fma_f32 v[152:153], v[0:1], v[182:183], v[152:153] op_sel_hi:[0,1,1]
	v_pk_fma_f32 v[154:155], v[0:1], v[186:187], v[154:155] op_sel_hi:[0,1,1]
	v_mov_b32_e32 v222, v221
	s_waitcnt lgkmcnt(2)
	v_pk_fma_f32 v[156:157], v[0:1], v[222:223], v[156:157] op_sel_hi:[0,1,1]
	ds_write2st64_b32 v33, v150, v151 offset0:128 offset1:136
	ds_write2st64_b32 v33, v152, v153 offset0:144 offset1:152
	ds_write2st64_b32 v33, v154, v155 offset0:160 offset1:168
	ds_write2st64_b32 v33, v156, v157 offset0:176 offset1:184
	v_pk_fma_f32 v[148:149], v[140:141], v[148:149], v[138:139] op_sel_hi:[0,1,0]
	v_pk_fma_f32 v[150:151], v[140:141], v[146:147], v[138:139] op_sel_hi:[0,1,0]
	v_pk_fma_f32 v[152:153], v[140:141], v[144:145], v[138:139] op_sel_hi:[0,1,0]
	v_pk_fma_f32 v[154:155], v[140:141], v[142:143], v[138:139] op_sel_hi:[0,1,0]
	v_pk_fma_f32 v[148:149], v[136:137], v[162:163], v[148:149] op_sel_hi:[0,1,1]
	v_pk_fma_f32 v[150:151], v[136:137], v[160:161], v[150:151] op_sel_hi:[0,1,1]
	v_pk_fma_f32 v[152:153], v[136:137], v[168:169], v[152:153] op_sel_hi:[0,1,1]
	v_pk_fma_f32 v[154:155], v[136:137], v[174:175], v[154:155] op_sel_hi:[0,1,1]
	v_pk_fma_f32 v[146:147], v[134:135], v[146:147], v[148:149] op_sel_hi:[0,1,1]
	v_pk_fma_f32 v[150:151], v[134:135], v[144:145], v[150:151] op_sel_hi:[0,1,1]
	v_pk_fma_f32 v[152:153], v[134:135], v[142:143], v[152:153] op_sel_hi:[0,1,1]
	v_pk_fma_f32 v[154:155], v[134:135], v[172:173], v[154:155] op_sel_hi:[0,1,1]
	v_pk_fma_f32 v[146:147], v[132:133], v[160:161], v[146:147] op_sel_hi:[0,1,1]
	v_pk_fma_f32 v[150:151], v[132:133], v[168:169], v[150:151] op_sel_hi:[0,1,1]
	v_pk_fma_f32 v[152:153], v[132:133], v[174:175], v[152:153] op_sel_hi:[0,1,1]
	v_pk_fma_f32 v[154:155], v[132:133], v[170:171], v[154:155] op_sel_hi:[0,1,1]
	v_pk_fma_f32 v[144:145], v[130:131], v[144:145], v[146:147] op_sel_hi:[0,1,1]
	v_pk_fma_f32 v[146:147], v[130:131], v[142:143], v[150:151] op_sel_hi:[0,1,1]
	v_pk_fma_f32 v[150:151], v[130:131], v[172:173], v[152:153] op_sel_hi:[0,1,1]
	v_pk_fma_f32 v[152:153], v[130:131], v[166:167], v[154:155] op_sel_hi:[0,1,1]
	v_pk_fma_f32 v[144:145], v[126:127], v[168:169], v[144:145] op_sel_hi:[0,1,1]
	v_pk_fma_f32 v[146:147], v[126:127], v[174:175], v[146:147] op_sel_hi:[0,1,1]
	v_pk_fma_f32 v[150:151], v[126:127], v[170:171], v[150:151] op_sel_hi:[0,1,1]
	v_pk_fma_f32 v[152:153], v[126:127], v[164:165], v[152:153] op_sel_hi:[0,1,1]
	v_pk_fma_f32 v[142:143], v[124:125], v[142:143], v[144:145] op_sel_hi:[0,1,1]
	v_pk_fma_f32 v[144:145], v[124:125], v[172:173], v[146:147] op_sel_hi:[0,1,1]
	v_pk_fma_f32 v[146:147], v[124:125], v[166:167], v[150:151] op_sel_hi:[0,1,1]
	v_pk_fma_f32 v[150:151], v[124:125], v[158:159], v[152:153] op_sel_hi:[0,1,1]
	v_pk_fma_f32 v[142:143], v[122:123], v[174:175], v[142:143] op_sel_hi:[0,1,1]
	v_pk_fma_f32 v[144:145], v[122:123], v[170:171], v[144:145] op_sel_hi:[0,1,1]
	v_pk_fma_f32 v[146:147], v[122:123], v[164:165], v[146:147] op_sel_hi:[0,1,1]
	v_pk_fma_f32 v[150:151], v[122:123], v[178:179], v[150:151] op_sel_hi:[0,1,1]
	v_pk_fma_f32 v[142:143], v[120:121], v[172:173], v[142:143] op_sel_hi:[0,1,1]
	v_pk_fma_f32 v[144:145], v[120:121], v[166:167], v[144:145] op_sel_hi:[0,1,1]
	v_pk_fma_f32 v[146:147], v[120:121], v[158:159], v[146:147] op_sel_hi:[0,1,1]
	v_pk_fma_f32 v[150:151], v[120:121], v[176:177], v[150:151] op_sel_hi:[0,1,1]
	v_pk_fma_f32 v[142:143], v[118:119], v[170:171], v[142:143] op_sel_hi:[0,1,1]
	v_pk_fma_f32 v[144:145], v[118:119], v[164:165], v[144:145] op_sel_hi:[0,1,1]
	v_pk_fma_f32 v[146:147], v[118:119], v[178:179], v[146:147] op_sel_hi:[0,1,1]
	v_pk_fma_f32 v[150:151], v[118:119], v[198:199], v[150:151] op_sel_hi:[0,1,1]
	v_pk_fma_f32 v[142:143], v[116:117], v[166:167], v[142:143] op_sel_hi:[0,1,1]
	v_pk_fma_f32 v[144:145], v[116:117], v[158:159], v[144:145] op_sel_hi:[0,1,1]
	v_pk_fma_f32 v[146:147], v[116:117], v[176:177], v[146:147] op_sel_hi:[0,1,1]
	v_pk_fma_f32 v[150:151], v[116:117], v[196:197], v[150:151] op_sel_hi:[0,1,1]
	v_pk_fma_f32 v[142:143], v[114:115], v[164:165], v[142:143] op_sel_hi:[0,1,1]
	v_pk_fma_f32 v[144:145], v[114:115], v[178:179], v[144:145] op_sel_hi:[0,1,1]
	v_pk_fma_f32 v[146:147], v[114:115], v[198:199], v[146:147] op_sel_hi:[0,1,1]
	v_pk_fma_f32 v[150:151], v[114:115], v[194:195], v[150:151] op_sel_hi:[0,1,1]
	v_pk_fma_f32 v[142:143], v[112:113], v[158:159], v[142:143] op_sel_hi:[0,1,1]
	v_pk_fma_f32 v[144:145], v[112:113], v[176:177], v[144:145] op_sel_hi:[0,1,1]
; __device__ __forceinline__ void conv_unit(LAS unsigned char* lds, int u, const bf16* PROJ, const float* conv_w, const float* conv_b, const float* ln_w, const float* ln_b, bf16* MIX, int tid, const WsRef& wsr) {
;     ...
;         for (int k = 0; k < 31; ++k) { const f2v wk = (f2v){w[k], w[k]};
; #pragma unroll
;             for (int t = 0; t < 4; ++t) y2[t] = __builtin_elementwise_fma(wk, (f2v){uw[2 * t + k], uw[2 * t + k + 1]}, y2[t]); }
; #pragma unroll
;         for (int t = 0; t < 4; ++t) { U[(tb * 8 + 2 * t) * 512 + tid] = y2[t].x; U[(tb * 8 + 2 * t + 1) * 512 + tid] = y2[t].y; }
;     }
;     __syncthreads();
	v_pk_fma_f32 v[146:147], v[112:113], v[196:197], v[146:147] op_sel_hi:[0,1,1]
	v_pk_fma_f32 v[150:151], v[112:113], v[192:193], v[150:151] op_sel_hi:[0,1,1]
	v_pk_fma_f32 v[142:143], v[110:111], v[178:179], v[142:143] op_sel_hi:[0,1,1]
	v_pk_fma_f32 v[144:145], v[110:111], v[198:199], v[144:145] op_sel_hi:[0,1,1]
	v_pk_fma_f32 v[146:147], v[110:111], v[194:195], v[146:147] op_sel_hi:[0,1,1]
	v_pk_fma_f32 v[150:151], v[110:111], v[190:191], v[150:151] op_sel_hi:[0,1,1]
	v_pk_fma_f32 v[142:143], v[108:109], v[176:177], v[142:143] op_sel_hi:[0,1,1]
	v_pk_fma_f32 v[144:145], v[108:109], v[196:197], v[144:145] op_sel_hi:[0,1,1]
	v_pk_fma_f32 v[146:147], v[108:109], v[192:193], v[146:147] op_sel_hi:[0,1,1]
	v_pk_fma_f32 v[150:151], v[108:109], v[188:189], v[150:151] op_sel_hi:[0,1,1]
	v_pk_fma_f32 v[142:143], v[106:107], v[198:199], v[142:143] op_sel_hi:[0,1,1]
	v_pk_fma_f32 v[144:145], v[106:107], v[194:195], v[144:145] op_sel_hi:[0,1,1]
	v_pk_fma_f32 v[146:147], v[106:107], v[190:191], v[146:147] op_sel_hi:[0,1,1]
	v_pk_fma_f32 v[150:151], v[106:107], v[202:203], v[150:151] op_sel_hi:[0,1,1]
	v_pk_fma_f32 v[142:143], v[104:105], v[196:197], v[142:143] op_sel_hi:[0,1,1]
	v_pk_fma_f32 v[144:145], v[104:105], v[192:193], v[144:145] op_sel_hi:[0,1,1]
	v_pk_fma_f32 v[146:147], v[104:105], v[188:189], v[146:147] op_sel_hi:[0,1,1]
	v_pk_fma_f32 v[150:151], v[104:105], v[200:201], v[150:151] op_sel_hi:[0,1,1]
	v_pk_fma_f32 v[142:143], v[102:103], v[194:195], v[142:143] op_sel_hi:[0,1,1]
	v_pk_fma_f32 v[144:145], v[102:103], v[190:191], v[144:145] op_sel_hi:[0,1,1]
	v_pk_fma_f32 v[146:147], v[102:103], v[202:203], v[146:147] op_sel_hi:[0,1,1]
	v_pk_fma_f32 v[150:151], v[102:103], v[180:181], v[150:151] op_sel_hi:[0,1,1]
	v_pk_fma_f32 v[142:143], v[100:101], v[192:193], v[142:143] op_sel_hi:[0,1,1]
	v_pk_fma_f32 v[144:145], v[100:101], v[188:189], v[144:145] op_sel_hi:[0,1,1]
	v_pk_fma_f32 v[146:147], v[100:101], v[200:201], v[146:147] op_sel_hi:[0,1,1]
	v_pk_fma_f32 v[150:151], v[100:101], v[182:183], v[150:151] op_sel_hi:[0,1,1]
	v_pk_fma_f32 v[142:143], v[98:99], v[190:191], v[142:143] op_sel_hi:[0,1,1]
	v_pk_fma_f32 v[144:145], v[98:99], v[202:203], v[144:145] op_sel_hi:[0,1,1]
	v_pk_fma_f32 v[146:147], v[98:99], v[180:181], v[146:147] op_sel_hi:[0,1,1]
	v_pk_fma_f32 v[150:151], v[98:99], v[184:185], v[150:151] op_sel_hi:[0,1,1]
	v_pk_fma_f32 v[142:143], v[96:97], v[188:189], v[142:143] op_sel_hi:[0,1,1]
	v_pk_fma_f32 v[144:145], v[96:97], v[200:201], v[144:145] op_sel_hi:[0,1,1]
	v_pk_fma_f32 v[146:147], v[96:97], v[182:183], v[146:147] op_sel_hi:[0,1,1]
	v_pk_fma_f32 v[150:151], v[96:97], v[186:187], v[150:151] op_sel_hi:[0,1,1]
	v_pk_fma_f32 v[142:143], v[94:95], v[202:203], v[142:143] op_sel_hi:[0,1,1]
	v_pk_fma_f32 v[144:145], v[94:95], v[180:181], v[144:145] op_sel_hi:[0,1,1]
	v_pk_fma_f32 v[146:147], v[94:95], v[184:185], v[146:147] op_sel_hi:[0,1,1]
	v_pk_fma_f32 v[150:151], v[94:95], v[220:221], v[150:151] op_sel_hi:[0,1,1]
	v_pk_fma_f32 v[142:143], v[92:93], v[200:201], v[142:143] op_sel_hi:[0,1,1]
	v_pk_fma_f32 v[144:145], v[92:93], v[182:183], v[144:145] op_sel_hi:[0,1,1]
	v_pk_fma_f32 v[146:147], v[92:93], v[186:187], v[146:147] op_sel_hi:[0,1,1]
	v_pk_fma_f32 v[150:151], v[92:93], v[222:223], v[150:151] op_sel_hi:[0,1,1]
	v_mov_b32_e32 v224, v223
	v_pk_fma_f32 v[142:143], v[90:91], v[180:181], v[142:143] op_sel_hi:[0,1,1]
	v_pk_fma_f32 v[144:145], v[90:91], v[184:185], v[144:145] op_sel_hi:[0,1,1]
	v_pk_fma_f32 v[146:147], v[90:91], v[220:221], v[146:147] op_sel_hi:[0,1,1]
	s_waitcnt lgkmcnt(5)
	v_pk_fma_f32 v[150:151], v[90:91], v[224:225], v[150:151] op_sel_hi:[0,1,1]
	v_mov_b32_e32 v226, v225
	ds_read_b32 v149, v129
	ds_read_b32 v157, v131
	ds_read_b32 v163, v133
	ds_read_b32 v7, v135
	ds_read_b32 v5, v137
	ds_read_b32 v3, v139
	v_pk_fma_f32 v[142:143], v[88:89], v[182:183], v[142:143] op_sel_hi:[0,1,1]
	v_pk_fma_f32 v[144:145], v[88:89], v[186:187], v[144:145] op_sel_hi:[0,1,1]
	v_pk_fma_f32 v[146:147], v[88:89], v[222:223], v[146:147] op_sel_hi:[0,1,1]
	s_waitcnt lgkmcnt(10)
	v_pk_fma_f32 v[150:151], v[88:89], v[226:227], v[150:151] op_sel_hi:[0,1,1]
	v_mov_b32_e32 v148, v227
	v_pk_fma_f32 v[142:143], v[86:87], v[184:185], v[142:143] op_sel_hi:[0,1,1]
	v_pk_fma_f32 v[144:145], v[86:87], v[220:221], v[144:145] op_sel_hi:[0,1,1]
	v_pk_fma_f32 v[146:147], v[86:87], v[224:225], v[146:147] op_sel_hi:[0,1,1]
	s_waitcnt lgkmcnt(5)
	v_pk_fma_f32 v[150:151], v[86:87], v[148:149], v[150:151] op_sel_hi:[0,1,1]
	v_mov_b32_e32 v156, v149
	v_pk_fma_f32 v[142:143], v[84:85], v[186:187], v[142:143] op_sel_hi:[0,1,1]
	v_pk_fma_f32 v[144:145], v[84:85], v[222:223], v[144:145] op_sel_hi:[0,1,1]
	v_pk_fma_f32 v[146:147], v[84:85], v[226:227], v[146:147] op_sel_hi:[0,1,1]
	s_waitcnt lgkmcnt(4)
	v_pk_fma_f32 v[150:151], v[84:85], v[156:157], v[150:151] op_sel_hi:[0,1,1]
	v_mov_b32_e32 v162, v157
	s_waitcnt lgkmcnt(2)
	v_pk_fma_f32 v[142:143], v[6:7], v[220:221], v[142:143] op_sel_hi:[0,1,1]
	v_pk_fma_f32 v[144:145], v[6:7], v[224:225], v[144:145] op_sel_hi:[0,1,1]
	v_pk_fma_f32 v[146:147], v[6:7], v[148:149], v[146:147] op_sel_hi:[0,1,1]
	v_pk_fma_f32 v[150:151], v[6:7], v[162:163], v[150:151] op_sel_hi:[0,1,1]
	v_mov_b32_e32 v6, v163
	s_waitcnt lgkmcnt(1)
	v_pk_fma_f32 v[142:143], v[4:5], v[222:223], v[142:143] op_sel_hi:[0,1,1]
	v_pk_fma_f32 v[144:145], v[4:5], v[226:227], v[144:145] op_sel_hi:[0,1,1]
	v_pk_fma_f32 v[146:147], v[4:5], v[156:157], v[146:147] op_sel_hi:[0,1,1]
	v_pk_fma_f32 v[150:151], v[4:5], v[6:7], v[150:151] op_sel_hi:[0,1,1]
	v_mov_b32_e32 v4, v7
	s_waitcnt lgkmcnt(0)
	v_pk_fma_f32 v[142:143], v[2:3], v[224:225], v[142:143] op_sel_hi:[0,1,1]
	v_pk_fma_f32 v[144:145], v[2:3], v[148:149], v[144:145] op_sel_hi:[0,1,1]
	v_pk_fma_f32 v[146:147], v[2:3], v[162:163], v[146:147] op_sel_hi:[0,1,1]
	v_pk_fma_f32 v[148:149], v[2:3], v[4:5], v[150:151] op_sel_hi:[0,1,1]
	v_mov_b32_e32 v2, v5
	v_pk_fma_f32 v[142:143], v[0:1], v[226:227], v[142:143] op_sel_hi:[0,1,1]
	v_pk_fma_f32 v[144:145], v[0:1], v[156:157], v[144:145] op_sel_hi:[0,1,1]
	v_pk_fma_f32 v[6:7], v[0:1], v[6:7], v[146:147] op_sel_hi:[0,1,1]
	v_pk_fma_f32 v[0:1], v[0:1], v[2:3], v[148:149] op_sel_hi:[0,1,1]
	ds_write2st64_b32 v33, v142, v143 offset0:192 offset1:200
	ds_write2st64_b32 v33, v144, v145 offset0:208 offset1:216
	ds_write2st64_b32 v33, v6, v7 offset0:224 offset1:232
	ds_write2st64_b32 v33, v0, v1 offset0:240 offset1:248
	s_waitcnt lgkmcnt(0)
	s_barrier
; #define LAS __attribute__((address_space(3)))
; __device__ __forceinline__ unsigned pk2(float lo, float hi) { return pg8::cvt_pk_bf16(lo, hi); }
; __device__ __forceinline__ void wt_store16(const WsRef& w, const void* p, u32x4 v) { __builtin_amdgcn_raw_buffer_store_b128(v, w.r, (unsigned)((const unsigned char*)p - w.base), 0, 16); }
; __device__ __forceinline__ void conv_unit(LAS unsigned char* lds, int u, const bf16* PROJ, const float* conv_w, const float* conv_b, const float* ln_w, const float* ln_b, bf16* MIX, int tid, const WsRef& wsr) {
;     ...
;     for (int i = 0; i < 4; ++i) { const int tt = wave * 4 + i;
;         const f32x4 a = *(const LAS f32x4*)(U + tt * 512 + lane * 8), b = *(const LAS f32x4*)(U + tt * 512 + lane * 8 + 4);
;         const float mu = wave_sum((a[0] + a[1]) + (a[2] + a[3]) + (b[0] + b[1]) + (b[2] + b[3])) * (1.f / 512.f);
;         const f32x4 da = a - mu, db = b - mu;
;         const float var = wave_sum((da[0] * da[0] + da[1] * da[1]) + (da[2] * da[2] + da[3] * da[3]) + (db[0] * db[0] + db[1] * db[1]) + (db[2] * db[2] + db[3] * db[3])) * (1.f / 512.f);
;         const float rstd = rsqrtf(var + EPS);
;         const f32x4 wa = *(const f32x4*)(ln_w + lane * 8), wb = *(const f32x4*)(ln_w + lane * 8 + 4), ba = *(const f32x4*)(ln_b + lane * 8), bb = *(const f32x4*)(ln_b + lane * 8 + 4);
;         f32x4 ya = da * rstd * wa + ba, yb = db * rstd * wb + bb;
; #pragma unroll
;         for (int e = 0; e < 4; ++e) { ya[e] = ya[e] * __builtin_amdgcn_rcpf(1.f + __expf(-ya[e])); yb[e] = yb[e] * __builtin_amdgcn_rcpf(1.f + __expf(-yb[e])); }
;         u32x4 o; o.x = pk2(ya[0], ya[1]); o.y = pk2(ya[2], ya[3]); o.z = pk2(yb[0], yb[1]); o.w = pk2(yb[2], yb[3]);
;         wt_store16(wsr, MIX + (rowb + t0 + tt) * D + 512 + lane * 8, o); }
	ds_read_b128 v[0:3], v212
	ds_read_b128 v[4:7], v212 offset:16
	s_waitcnt lgkmcnt(1)
	v_mov_b32_e32 v142, v1
	v_mov_b32_e32 v143, v2
	v_mov_b32_e32 v144, v0
	v_mov_b32_e32 v145, v3
	v_pk_add_f32 v[142:143], v[142:143], v[144:145]
	s_waitcnt lgkmcnt(0)
	v_mov_b32_e32 v144, v6
	v_mov_b32_e32 v145, v4
	v_mov_b32_e32 v146, v7
	v_mov_b32_e32 v147, v5
	v_pk_add_f32 v[144:145], v[144:145], v[146:147]
	v_add_f32_e32 v84, v142, v143
	v_add_f32_e32 v84, v84, v145
	v_add_f32_e32 v84, v144, v84
	ds_bpermute_b32 v86, v141, v84
	global_load_dwordx4 v[142:145], v[78:79], off
	global_load_dwordx4 v[146:149], v[76:77], off
	global_load_dwordx4 v[150:153], v[76:77], off offset:16
	global_load_dwordx4 v[154:157], v[78:79], off offset:16
	s_waitcnt lgkmcnt(0)
	v_add_f32_e32 v84, v84, v86
	ds_bpermute_b32 v86, v205, v84
	s_waitcnt lgkmcnt(0)
	v_add_f32_e32 v84, v84, v86
	ds_bpermute_b32 v86, v206, v84
	s_waitcnt lgkmcnt(0)
	v_add_f32_e32 v84, v84, v86
	ds_bpermute_b32 v86, v207, v84
	s_waitcnt lgkmcnt(0)
	v_add_f32_e32 v84, v84, v86
	ds_bpermute_b32 v86, v208, v84
	s_waitcnt lgkmcnt(0)
	v_add_f32_e32 v84, v84, v86
	ds_bpermute_b32 v86, v209, v84
	s_waitcnt lgkmcnt(0)
	v_add_f32_e32 v84, v84, v86
	v_fmamk_f32 v1, v84, 0xbb000000, v1
	v_fmamk_f32 v0, v84, 0xbb000000, v0
	v_fmamk_f32 v3, v84, 0xbb000000, v3
	v_fmac_f32_e32 v2, 0xbb000000, v84
	v_pk_mul_f32 v[158:159], v[2:3], v[2:3]
	v_pk_mul_f32 v[160:161], v[0:1], v[0:1]
	v_fmamk_f32 v5, v84, 0xbb000000, v5
	v_fmamk_f32 v4, v84, 0xbb000000, v4
	v_fmamk_f32 v7, v84, 0xbb000000, v7
	v_fmac_f32_e32 v6, 0xbb000000, v84
	v_pk_mov_b32 v[162:163], v[160:161], v[158:159] op_sel:[1,0]
	v_mov_b32_e32 v161, v159
	v_pk_add_f32 v[158:159], v[162:163], v[160:161]
	v_pk_mul_f32 v[160:161], v[6:7], v[6:7]
	v_pk_mul_f32 v[162:163], v[4:5], v[4:5]
	v_mov_b32_e32 v164, v160
	v_mov_b32_e32 v165, v162
	v_mov_b32_e32 v162, v161
	v_pk_add_f32 v[160:161], v[164:165], v[162:163]
	v_add_f32_e32 v84, v158, v159
	v_add_f32_e32 v84, v161, v84
	v_add_f32_e32 v84, v160, v84
	ds_bpermute_b32 v86, v141, v84
	s_waitcnt lgkmcnt(0)
	v_add_f32_e32 v84, v84, v86
	ds_bpermute_b32 v86, v205, v84
	s_waitcnt lgkmcnt(0)
	v_add_f32_e32 v84, v84, v86
	ds_bpermute_b32 v86, v206, v84
	s_waitcnt lgkmcnt(0)
	v_add_f32_e32 v84, v84, v86
	ds_bpermute_b32 v86, v207, v84
	s_waitcnt lgkmcnt(0)
	v_add_f32_e32 v84, v84, v86
	ds_bpermute_b32 v86, v208, v84
	s_waitcnt lgkmcnt(0)
	v_add_f32_e32 v84, v84, v86
	ds_bpermute_b32 v86, v209, v84
	s_waitcnt lgkmcnt(0)
	v_add_f32_e32 v84, v84, v86
	v_fmamk_f32 v84, v84, 0x3b000000, v213
	v_mul_f32_e32 v86, 0x4b800000, v84
	v_cmp_gt_f32_e32 vcc, s27, v84
	s_nop 1
	v_cndmask_b32_e32 v84, v84, v86, vcc
	v_rsq_f32_e32 v84, v84
	s_nop 0
	v_mul_f32_e32 v86, 0x45800000, v84
	v_cndmask_b32_e32 v84, v84, v86, vcc
	v_pk_mul_f32 v[0:1], v[0:1], v[84:85] op_sel_hi:[1,0]
	v_pk_mul_f32 v[2:3], v[2:3], v[84:85] op_sel_hi:[1,0]
	s_waitcnt vmcnt(2)
	v_pk_fma_f32 v[142:143], v[146:147], v[0:1], v[142:143]
	v_pk_mul_f32 v[0:1], v[4:5], v[84:85] op_sel_hi:[1,0]
	v_pk_fma_f32 v[144:145], v[148:149], v[2:3], v[144:145]
	s_waitcnt vmcnt(0)
	v_pk_fma_f32 v[146:147], v[150:151], v[0:1], v[154:155]
	v_mul_f32_e32 v0, 0xbfb8aa3b, v142
	v_exp_f32_e32 v0, v0
	v_mul_f32_e32 v1, 0xbfb8aa3b, v146
	v_exp_f32_e32 v1, v1
	v_pk_mul_f32 v[2:3], v[6:7], v[84:85] op_sel_hi:[1,0]
	v_add_f32_e32 v0, 1.0, v0
	v_rcp_f32_e32 v150, v0
	v_add_f32_e32 v0, 1.0, v1
	v_mul_f32_e32 v1, 0xbfb8aa3b, v143
	v_pk_fma_f32 v[148:149], v[152:153], v[2:3], v[156:157]
	v_exp_f32_e32 v1, v1
	v_mul_f32_e32 v2, 0xbfb8aa3b, v147
	v_exp_f32_e32 v2, v2
	v_rcp_f32_e32 v152, v0
	v_add_f32_e32 v0, 1.0, v1
	v_mul_f32_e32 v1, 0xbfb8aa3b, v144
	v_rcp_f32_e32 v151, v0
	v_add_f32_e32 v0, 1.0, v2
	v_exp_f32_e32 v1, v1
	v_mul_f32_e32 v2, 0xbfb8aa3b, v148
	v_exp_f32_e32 v2, v2
	v_rcp_f32_e32 v153, v0
	v_add_f32_e32 v0, 1.0, v1
	v_rcp_f32_e32 v154, v0
	v_add_f32_e32 v0, 1.0, v2
	v_mul_f32_e32 v4, 0xbfb8aa3b, v145
	v_rcp_f32_e32 v156, v0
	ds_read_b128 v[0:3], v215
	v_exp_f32_e32 v84, v4
	v_mul_f32_e32 v4, 0xbfb8aa3b, v149
	v_exp_f32_e32 v86, v4
	ds_read_b128 v[4:7], v215 offset:16
	s_waitcnt lgkmcnt(1)
	v_mov_b32_e32 v158, v1
	v_mov_b32_e32 v159, v2
	v_mov_b32_e32 v160, v0
	v_mov_b32_e32 v161, v3
	v_pk_add_f32 v[158:159], v[158:159], v[160:161]
	s_waitcnt lgkmcnt(0)
	v_mov_b32_e32 v160, v6
	v_mov_b32_e32 v161, v4
	v_mov_b32_e32 v162, v7
	v_mov_b32_e32 v163, v5
	v_pk_add_f32 v[160:161], v[160:161], v[162:163]
	v_add_f32_e32 v88, v158, v159
	v_add_f32_e32 v88, v88, v161
	v_add_f32_e32 v88, v160, v88
	ds_bpermute_b32 v90, v141, v88
	v_add_f32_e32 v84, 1.0, v84
	v_rcp_f32_e32 v155, v84
	v_add_f32_e32 v84, 1.0, v86
	v_rcp_f32_e32 v157, v84
	s_waitcnt lgkmcnt(0)
	v_add_f32_e32 v84, v88, v90
	ds_bpermute_b32 v86, v205, v84
	v_add_lshl_u32 v88, s3, v74, 11
	v_pk_mul_f32 v[142:143], v[142:143], v[150:151]
	v_pk_mul_f32 v[146:147], v[146:147], v[152:153]
	v_pk_mul_f32 v[144:145], v[144:145], v[154:155]
	v_pk_mul_f32 v[148:149], v[148:149], v[156:157]
	v_add3_u32 v88, s70, v88, v214
	v_cvt_pk_bf16_f32 v142, v142, v143
	v_cvt_pk_bf16_f32 v143, v144, v145
	v_cvt_pk_bf16_f32 v144, v146, v147
	v_cvt_pk_bf16_f32 v145, v148, v149
	v_subrev_u32_e32 v88, s84, v88
	buffer_store_dwordx4 v[142:145], v88, s[88:91], 0 offen offset:1024 sc1
	s_waitcnt lgkmcnt(0)
	v_add_f32_e32 v84, v84, v86
	global_load_dwordx4 v[142:145], v[78:79], off
	global_load_dwordx4 v[146:149], v[76:77], off
	global_load_dwordx4 v[150:153], v[76:77], off offset:16
	global_load_dwordx4 v[154:157], v[78:79], off offset:16
	ds_bpermute_b32 v86, v206, v84
	s_waitcnt lgkmcnt(0)
	v_add_f32_e32 v84, v84, v86
	ds_bpermute_b32 v86, v207, v84
	s_waitcnt lgkmcnt(0)
; #define LAS __attribute__((address_space(3)))
; __device__ __forceinline__ unsigned pk2(float lo, float hi) { return pg8::cvt_pk_bf16(lo, hi); }
; __device__ __forceinline__ void wt_store16(const WsRef& w, const void* p, u32x4 v) { __builtin_amdgcn_raw_buffer_store_b128(v, w.r, (unsigned)((const unsigned char*)p - w.base), 0, 16); }
; __device__ __forceinline__ void conv_unit(LAS unsigned char* lds, int u, const bf16* PROJ, const float* conv_w, const float* conv_b, const float* ln_w, const float* ln_b, bf16* MIX, int tid, const WsRef& wsr) {
;     ...
;     for (int i = 0; i < 4; ++i) { const int tt = wave * 4 + i;
;         const f32x4 a = *(const LAS f32x4*)(U + tt * 512 + lane * 8), b = *(const LAS f32x4*)(U + tt * 512 + lane * 8 + 4);
;         const float mu = wave_sum((a[0] + a[1]) + (a[2] + a[3]) + (b[0] + b[1]) + (b[2] + b[3])) * (1.f / 512.f);
;         const f32x4 da = a - mu, db = b - mu;
;         const float var = wave_sum((da[0] * da[0] + da[1] * da[1]) + (da[2] * da[2] + da[3] * da[3]) + (db[0] * db[0] + db[1] * db[1]) + (db[2] * db[2] + db[3] * db[3])) * (1.f / 512.f);
;         const float rstd = rsqrtf(var + EPS);
;         const f32x4 wa = *(const f32x4*)(ln_w + lane * 8), wb = *(const f32x4*)(ln_w + lane * 8 + 4), ba = *(const f32x4*)(ln_b + lane * 8), bb = *(const f32x4*)(ln_b + lane * 8 + 4);
;         f32x4 ya = da * rstd * wa + ba, yb = db * rstd * wb + bb;
; #pragma unroll
;         for (int e = 0; e < 4; ++e) { ya[e] = ya[e] * __builtin_amdgcn_rcpf(1.f + __expf(-ya[e])); yb[e] = yb[e] * __builtin_amdgcn_rcpf(1.f + __expf(-yb[e])); }
;         u32x4 o; o.x = pk2(ya[0], ya[1]); o.y = pk2(ya[2], ya[3]); o.z = pk2(yb[0], yb[1]); o.w = pk2(yb[2], yb[3]);
;         wt_store16(wsr, MIX + (rowb + t0 + tt) * D + 512 + lane * 8, o); }
	v_add_f32_e32 v84, v84, v86
	ds_bpermute_b32 v86, v208, v84
	s_waitcnt lgkmcnt(0)
	v_add_f32_e32 v84, v84, v86
	ds_bpermute_b32 v86, v209, v84
	s_waitcnt lgkmcnt(0)
	v_add_f32_e32 v84, v84, v86
	v_fmamk_f32 v1, v84, 0xbb000000, v1
	v_fmamk_f32 v0, v84, 0xbb000000, v0
	v_fmamk_f32 v3, v84, 0xbb000000, v3
	v_fmac_f32_e32 v2, 0xbb000000, v84
	v_pk_mul_f32 v[158:159], v[2:3], v[2:3]
	v_pk_mul_f32 v[160:161], v[0:1], v[0:1]
	v_fmamk_f32 v5, v84, 0xbb000000, v5
	v_fmamk_f32 v4, v84, 0xbb000000, v4
	v_fmamk_f32 v7, v84, 0xbb000000, v7
	v_fmac_f32_e32 v6, 0xbb000000, v84
	v_pk_mov_b32 v[162:163], v[160:161], v[158:159] op_sel:[1,0]
	v_mov_b32_e32 v161, v159
	v_pk_add_f32 v[158:159], v[162:163], v[160:161]
	v_pk_mul_f32 v[160:161], v[6:7], v[6:7]
	v_pk_mul_f32 v[162:163], v[4:5], v[4:5]
	v_mov_b32_e32 v164, v160
	v_mov_b32_e32 v165, v162
	v_mov_b32_e32 v162, v161
	v_pk_add_f32 v[160:161], v[164:165], v[162:163]
	v_add_f32_e32 v84, v158, v159
	v_add_f32_e32 v84, v161, v84
	v_add_f32_e32 v84, v160, v84
	ds_bpermute_b32 v86, v141, v84
	s_waitcnt lgkmcnt(0)
	v_add_f32_e32 v84, v84, v86
	ds_bpermute_b32 v86, v205, v84
	s_waitcnt lgkmcnt(0)
	v_add_f32_e32 v84, v84, v86
	ds_bpermute_b32 v86, v206, v84
	s_waitcnt lgkmcnt(0)
	v_add_f32_e32 v84, v84, v86
	ds_bpermute_b32 v86, v207, v84
	s_waitcnt lgkmcnt(0)
	v_add_f32_e32 v84, v84, v86
	ds_bpermute_b32 v86, v208, v84
	s_waitcnt lgkmcnt(0)
	v_add_f32_e32 v84, v84, v86
	ds_bpermute_b32 v86, v209, v84
	s_waitcnt lgkmcnt(0)
	v_add_f32_e32 v84, v84, v86
	v_fmamk_f32 v84, v84, 0x3b000000, v213
	v_mul_f32_e32 v86, 0x4b800000, v84
	v_cmp_gt_f32_e32 vcc, s27, v84
	s_nop 1
	v_cndmask_b32_e32 v84, v84, v86, vcc
	v_rsq_f32_e32 v84, v84
	s_nop 0
	v_mul_f32_e32 v86, 0x45800000, v84
	v_cndmask_b32_e32 v84, v84, v86, vcc
	v_pk_mul_f32 v[0:1], v[0:1], v[84:85] op_sel_hi:[1,0]
	v_pk_mul_f32 v[2:3], v[2:3], v[84:85] op_sel_hi:[1,0]
	s_waitcnt vmcnt(2)
	v_pk_fma_f32 v[142:143], v[146:147], v[0:1], v[142:143]
	v_pk_mul_f32 v[0:1], v[4:5], v[84:85] op_sel_hi:[1,0]
	v_pk_fma_f32 v[144:145], v[148:149], v[2:3], v[144:145]
	s_waitcnt vmcnt(0)
	v_pk_fma_f32 v[146:147], v[150:151], v[0:1], v[154:155]
	v_mul_f32_e32 v0, 0xbfb8aa3b, v142
	v_exp_f32_e32 v0, v0
	v_mul_f32_e32 v1, 0xbfb8aa3b, v146
	v_exp_f32_e32 v1, v1
	v_pk_mul_f32 v[2:3], v[6:7], v[84:85] op_sel_hi:[1,0]
	v_add_f32_e32 v0, 1.0, v0
	v_rcp_f32_e32 v150, v0
	v_add_f32_e32 v0, 1.0, v1
	v_mul_f32_e32 v1, 0xbfb8aa3b, v143
	v_pk_fma_f32 v[148:149], v[152:153], v[2:3], v[156:157]
	v_exp_f32_e32 v1, v1
	v_mul_f32_e32 v2, 0xbfb8aa3b, v147
	v_exp_f32_e32 v2, v2
	v_rcp_f32_e32 v152, v0
	v_add_f32_e32 v0, 1.0, v1
	v_mul_f32_e32 v1, 0xbfb8aa3b, v144
	v_rcp_f32_e32 v151, v0
	v_add_f32_e32 v0, 1.0, v2
	v_exp_f32_e32 v1, v1
	v_mul_f32_e32 v2, 0xbfb8aa3b, v148
	v_exp_f32_e32 v2, v2
	v_rcp_f32_e32 v153, v0
	v_add_f32_e32 v0, 1.0, v1
	v_rcp_f32_e32 v154, v0
	v_add_f32_e32 v0, 1.0, v2
	v_mul_f32_e32 v4, 0xbfb8aa3b, v145
	v_rcp_f32_e32 v156, v0
	ds_read_b128 v[0:3], v216
	v_exp_f32_e32 v84, v4
	v_mul_f32_e32 v4, 0xbfb8aa3b, v149
	v_exp_f32_e32 v86, v4
	ds_read_b128 v[4:7], v216 offset:16
	s_waitcnt lgkmcnt(1)
	v_mov_b32_e32 v158, v1
	v_mov_b32_e32 v159, v2
	v_mov_b32_e32 v160, v0
	v_mov_b32_e32 v161, v3
	v_pk_add_f32 v[158:159], v[158:159], v[160:161]
	s_waitcnt lgkmcnt(0)
	v_mov_b32_e32 v160, v6
	v_mov_b32_e32 v161, v4
	v_mov_b32_e32 v162, v7
	v_mov_b32_e32 v163, v5
	v_pk_add_f32 v[160:161], v[160:161], v[162:163]
	v_add_f32_e32 v88, v158, v159
	v_add_f32_e32 v88, v88, v161
	v_add_f32_e32 v88, v160, v88
	ds_bpermute_b32 v90, v141, v88
	v_add_f32_e32 v84, 1.0, v84
	v_rcp_f32_e32 v155, v84
	v_add_f32_e32 v84, 1.0, v86
	v_rcp_f32_e32 v157, v84
	s_waitcnt lgkmcnt(0)
	v_add_f32_e32 v84, v88, v90
	ds_bpermute_b32 v86, v205, v84
	v_add_lshl_u32 v88, s3, v80, 11
	v_pk_mul_f32 v[142:143], v[142:143], v[150:151]
	v_pk_mul_f32 v[146:147], v[146:147], v[152:153]
	v_pk_mul_f32 v[144:145], v[144:145], v[154:155]
	v_pk_mul_f32 v[148:149], v[148:149], v[156:157]
	v_add3_u32 v88, s70, v88, v214
	v_cvt_pk_bf16_f32 v142, v142, v143
	v_cvt_pk_bf16_f32 v143, v144, v145
	v_cvt_pk_bf16_f32 v144, v146, v147
	v_cvt_pk_bf16_f32 v145, v148, v149
	v_subrev_u32_e32 v88, s84, v88
	buffer_store_dwordx4 v[142:145], v88, s[88:91], 0 offen offset:1024 sc1
	s_waitcnt lgkmcnt(0)
	v_add_f32_e32 v84, v84, v86
	global_load_dwordx4 v[142:145], v[78:79], off
	global_load_dwordx4 v[146:149], v[76:77], off
	global_load_dwordx4 v[150:153], v[76:77], off offset:16
	global_load_dwordx4 v[154:157], v[78:79], off offset:16
	ds_bpermute_b32 v86, v206, v84
	s_waitcnt lgkmcnt(0)
	v_add_f32_e32 v84, v84, v86
	ds_bpermute_b32 v86, v207, v84
	s_waitcnt lgkmcnt(0)
	v_add_f32_e32 v84, v84, v86
	ds_bpermute_b32 v86, v208, v84
	s_waitcnt lgkmcnt(0)
	v_add_f32_e32 v84, v84, v86
	ds_bpermute_b32 v86, v209, v84
	s_waitcnt lgkmcnt(0)
	v_add_f32_e32 v84, v84, v86
	v_fmamk_f32 v1, v84, 0xbb000000, v1
	v_fmamk_f32 v0, v84, 0xbb000000, v0
	v_fmamk_f32 v3, v84, 0xbb000000, v3
	v_fmac_f32_e32 v2, 0xbb000000, v84
	v_pk_mul_f32 v[158:159], v[2:3], v[2:3]
	v_pk_mul_f32 v[160:161], v[0:1], v[0:1]
	v_fmamk_f32 v5, v84, 0xbb000000, v5
	v_fmamk_f32 v4, v84, 0xbb000000, v4
	v_fmamk_f32 v7, v84, 0xbb000000, v7
	v_fmac_f32_e32 v6, 0xbb000000, v84
	v_pk_mov_b32 v[162:163], v[160:161], v[158:159] op_sel:[1,0]
	v_mov_b32_e32 v161, v159
	v_pk_add_f32 v[158:159], v[162:163], v[160:161]
	v_pk_mul_f32 v[160:161], v[6:7], v[6:7]
	v_pk_mul_f32 v[162:163], v[4:5], v[4:5]
	v_mov_b32_e32 v164, v160
	v_mov_b32_e32 v165, v162
	v_mov_b32_e32 v162, v161
	v_pk_add_f32 v[160:161], v[164:165], v[162:163]
	v_add_f32_e32 v84, v158, v159
	v_add_f32_e32 v84, v161, v84
	v_add_f32_e32 v84, v160, v84
	ds_bpermute_b32 v86, v141, v84
	s_waitcnt lgkmcnt(0)
; #define LAS __attribute__((address_space(3)))
; __device__ __forceinline__ unsigned pk2(float lo, float hi) { return pg8::cvt_pk_bf16(lo, hi); }
; __device__ __forceinline__ void wt_store16(const WsRef& w, const void* p, u32x4 v) { __builtin_amdgcn_raw_buffer_store_b128(v, w.r, (unsigned)((const unsigned char*)p - w.base), 0, 16); }
; __device__ __forceinline__ void conv_unit(LAS unsigned char* lds, int u, const bf16* PROJ, const float* conv_w, const float* conv_b, const float* ln_w, const float* ln_b, bf16* MIX, int tid, const WsRef& wsr) {
;     ...
;     for (int i = 0; i < 4; ++i) { const int tt = wave * 4 + i;
;         const f32x4 a = *(const LAS f32x4*)(U + tt * 512 + lane * 8), b = *(const LAS f32x4*)(U + tt * 512 + lane * 8 + 4);
;         const float mu = wave_sum((a[0] + a[1]) + (a[2] + a[3]) + (b[0] + b[1]) + (b[2] + b[3])) * (1.f / 512.f);
;         const f32x4 da = a - mu, db = b - mu;
;         const float var = wave_sum((da[0] * da[0] + da[1] * da[1]) + (da[2] * da[2] + da[3] * da[3]) + (db[0] * db[0] + db[1] * db[1]) + (db[2] * db[2] + db[3] * db[3])) * (1.f / 512.f);
;         const float rstd = rsqrtf(var + EPS);
;         const f32x4 wa = *(const f32x4*)(ln_w + lane * 8), wb = *(const f32x4*)(ln_w + lane * 8 + 4), ba = *(const f32x4*)(ln_b + lane * 8), bb = *(const f32x4*)(ln_b + lane * 8 + 4);
;         f32x4 ya = da * rstd * wa + ba, yb = db * rstd * wb + bb;
; #pragma unroll
;         for (int e = 0; e < 4; ++e) { ya[e] = ya[e] * __builtin_amdgcn_rcpf(1.f + __expf(-ya[e])); yb[e] = yb[e] * __builtin_amdgcn_rcpf(1.f + __expf(-yb[e])); }
;         u32x4 o; o.x = pk2(ya[0], ya[1]); o.y = pk2(ya[2], ya[3]); o.z = pk2(yb[0], yb[1]); o.w = pk2(yb[2], yb[3]);
;         wt_store16(wsr, MIX + (rowb + t0 + tt) * D + 512 + lane * 8, o); }
	v_add_f32_e32 v84, v84, v86
	ds_bpermute_b32 v86, v205, v84
	s_waitcnt lgkmcnt(0)
	v_add_f32_e32 v84, v84, v86
	ds_bpermute_b32 v86, v206, v84
	s_waitcnt lgkmcnt(0)
	v_add_f32_e32 v84, v84, v86
	ds_bpermute_b32 v86, v207, v84
	s_waitcnt lgkmcnt(0)
	v_add_f32_e32 v84, v84, v86
	ds_bpermute_b32 v86, v208, v84
	s_waitcnt lgkmcnt(0)
	v_add_f32_e32 v84, v84, v86
	ds_bpermute_b32 v86, v209, v84
	s_waitcnt lgkmcnt(0)
	v_add_f32_e32 v84, v84, v86
	v_fmamk_f32 v84, v84, 0x3b000000, v213
	v_mul_f32_e32 v86, 0x4b800000, v84
	v_cmp_gt_f32_e32 vcc, s27, v84
	s_nop 1
	v_cndmask_b32_e32 v84, v84, v86, vcc
	v_rsq_f32_e32 v84, v84
	s_nop 0
	v_mul_f32_e32 v86, 0x45800000, v84
	v_cndmask_b32_e32 v84, v84, v86, vcc
	v_pk_mul_f32 v[0:1], v[0:1], v[84:85] op_sel_hi:[1,0]
	v_pk_mul_f32 v[2:3], v[2:3], v[84:85] op_sel_hi:[1,0]
	s_waitcnt vmcnt(2)
	v_pk_fma_f32 v[142:143], v[146:147], v[0:1], v[142:143]
	v_pk_mul_f32 v[0:1], v[4:5], v[84:85] op_sel_hi:[1,0]
	v_pk_fma_f32 v[144:145], v[148:149], v[2:3], v[144:145]
	s_waitcnt vmcnt(0)
	v_pk_fma_f32 v[146:147], v[150:151], v[0:1], v[154:155]
	v_mul_f32_e32 v0, 0xbfb8aa3b, v142
	v_exp_f32_e32 v0, v0
	v_mul_f32_e32 v1, 0xbfb8aa3b, v146
	v_exp_f32_e32 v1, v1
	v_pk_mul_f32 v[2:3], v[6:7], v[84:85] op_sel_hi:[1,0]
	v_add_f32_e32 v0, 1.0, v0
	v_rcp_f32_e32 v150, v0
	v_add_f32_e32 v0, 1.0, v1
	v_mul_f32_e32 v1, 0xbfb8aa3b, v143
	v_pk_fma_f32 v[148:149], v[152:153], v[2:3], v[156:157]
	v_exp_f32_e32 v1, v1
	v_mul_f32_e32 v2, 0xbfb8aa3b, v147
	v_exp_f32_e32 v2, v2
	v_rcp_f32_e32 v152, v0
	v_add_f32_e32 v0, 1.0, v1
	v_mul_f32_e32 v1, 0xbfb8aa3b, v144
	v_rcp_f32_e32 v151, v0
	v_add_f32_e32 v0, 1.0, v2
	v_exp_f32_e32 v1, v1
	v_mul_f32_e32 v2, 0xbfb8aa3b, v148
	v_exp_f32_e32 v2, v2
	v_rcp_f32_e32 v153, v0
	v_add_f32_e32 v0, 1.0, v1
	v_rcp_f32_e32 v154, v0
	v_add_f32_e32 v0, 1.0, v2
	v_mul_f32_e32 v4, 0xbfb8aa3b, v145
	v_rcp_f32_e32 v156, v0
	ds_read_b128 v[0:3], v217
	v_exp_f32_e32 v84, v4
	v_mul_f32_e32 v4, 0xbfb8aa3b, v149
	v_exp_f32_e32 v86, v4
	ds_read_b128 v[4:7], v217 offset:16
	s_waitcnt lgkmcnt(1)
	v_mov_b32_e32 v158, v1
	v_mov_b32_e32 v159, v2
	v_mov_b32_e32 v160, v0
	v_mov_b32_e32 v161, v3
	v_pk_add_f32 v[158:159], v[158:159], v[160:161]
	s_waitcnt lgkmcnt(0)
	v_mov_b32_e32 v160, v6
	v_mov_b32_e32 v161, v4
	v_mov_b32_e32 v162, v7
	v_mov_b32_e32 v163, v5
	v_pk_add_f32 v[160:161], v[160:161], v[162:163]
	v_add_f32_e32 v88, v158, v159
	v_add_f32_e32 v88, v88, v161
	v_add_f32_e32 v88, v160, v88
	ds_bpermute_b32 v90, v141, v88
	v_add_f32_e32 v84, 1.0, v84
	v_rcp_f32_e32 v155, v84
	v_add_f32_e32 v84, 1.0, v86
	v_rcp_f32_e32 v157, v84
	s_waitcnt lgkmcnt(0)
	v_add_f32_e32 v84, v88, v90
	ds_bpermute_b32 v86, v205, v84
	v_add_lshl_u32 v88, s3, v82, 11
	v_pk_mul_f32 v[142:143], v[142:143], v[150:151]
	v_pk_mul_f32 v[146:147], v[146:147], v[152:153]
	v_pk_mul_f32 v[144:145], v[144:145], v[154:155]
	v_pk_mul_f32 v[148:149], v[148:149], v[156:157]
	v_add3_u32 v88, s70, v88, v214
	v_cvt_pk_bf16_f32 v142, v142, v143
	v_cvt_pk_bf16_f32 v143, v144, v145
	v_cvt_pk_bf16_f32 v144, v146, v147
	v_cvt_pk_bf16_f32 v145, v148, v149
	v_subrev_u32_e32 v88, s84, v88
	buffer_store_dwordx4 v[142:145], v88, s[88:91], 0 offen offset:1024 sc1
	s_waitcnt lgkmcnt(0)
	v_add_f32_e32 v84, v84, v86
	global_load_dwordx4 v[142:145], v[78:79], off
	global_load_dwordx4 v[146:149], v[76:77], off
	global_load_dwordx4 v[150:153], v[76:77], off offset:16
	global_load_dwordx4 v[154:157], v[78:79], off offset:16
	ds_bpermute_b32 v86, v206, v84
	s_waitcnt lgkmcnt(0)
	v_add_f32_e32 v84, v84, v86
	ds_bpermute_b32 v86, v207, v84
	s_waitcnt lgkmcnt(0)
	v_add_f32_e32 v84, v84, v86
	ds_bpermute_b32 v86, v208, v84
	s_waitcnt lgkmcnt(0)
	v_add_f32_e32 v84, v84, v86
	ds_bpermute_b32 v86, v209, v84
	s_waitcnt lgkmcnt(0)
	v_add_f32_e32 v84, v84, v86
	v_fmamk_f32 v1, v84, 0xbb000000, v1
	v_fmamk_f32 v0, v84, 0xbb000000, v0
	v_fmamk_f32 v3, v84, 0xbb000000, v3
	v_fmac_f32_e32 v2, 0xbb000000, v84
	v_pk_mul_f32 v[158:159], v[2:3], v[2:3]
	v_pk_mul_f32 v[160:161], v[0:1], v[0:1]
	v_fmamk_f32 v5, v84, 0xbb000000, v5
	v_fmamk_f32 v4, v84, 0xbb000000, v4
	v_fmamk_f32 v7, v84, 0xbb000000, v7
	v_fmac_f32_e32 v6, 0xbb000000, v84
	v_pk_mov_b32 v[162:163], v[160:161], v[158:159] op_sel:[1,0]
	v_mov_b32_e32 v161, v159
	v_pk_add_f32 v[158:159], v[162:163], v[160:161]
	v_pk_mul_f32 v[160:161], v[6:7], v[6:7]
	v_pk_mul_f32 v[162:163], v[4:5], v[4:5]
	v_mov_b32_e32 v164, v160
	v_mov_b32_e32 v165, v162
	v_mov_b32_e32 v162, v161
	v_pk_add_f32 v[160:161], v[164:165], v[162:163]
	v_add_f32_e32 v84, v158, v159
	v_add_f32_e32 v84, v161, v84
	v_add_f32_e32 v84, v160, v84
	ds_bpermute_b32 v86, v141, v84
	s_waitcnt lgkmcnt(0)
	v_add_f32_e32 v84, v84, v86
	ds_bpermute_b32 v86, v205, v84
	s_waitcnt lgkmcnt(0)
	v_add_f32_e32 v84, v84, v86
	ds_bpermute_b32 v86, v206, v84
	s_waitcnt lgkmcnt(0)
	v_add_f32_e32 v84, v84, v86
	ds_bpermute_b32 v86, v207, v84
	s_waitcnt lgkmcnt(0)
	v_add_f32_e32 v84, v84, v86
	ds_bpermute_b32 v86, v208, v84
	s_waitcnt lgkmcnt(0)
	v_add_f32_e32 v84, v84, v86
	ds_bpermute_b32 v86, v209, v84
	s_waitcnt lgkmcnt(0)
; __device__ __forceinline__ void conv_unit(LAS unsigned char* lds, int u, const bf16* PROJ, const float* conv_w, const float* conv_b, const float* ln_w, const float* ln_b, bf16* MIX, int tid, const WsRef& wsr) {
;     ...
;     const int t0 = (u * 32) % SEQ; const size_t rowb = (size_t)(u * 32 / SEQ) * SEQ;
;     for (int it = tid; it < 62 * 64; it += 512) { const int r = it >> 6, cc = it & 63; const int t = t0 - 15 + r;
;         f32x4 u0 = (f32x4){0.f, 0.f, 0.f, 0.f}, u1 = u0;
;         if (t >= 0 && t < SEQ) { const bf16* pr = PROJ + (rowb + t) * INC + 2048 + cc * 8; const u32x4 a = *(const u32x4*)pr, g = *(const u32x4*)(pr + 512);
; #pragma unroll
;             for (int e = 0; e < 4; ++e) { const float a0 = bflo(a[e]), a1 = bfhi(a[e]), g0 = bflo(g[e]), g1 = bfhi(g[e]);
;                 const float v0 = a0 * __builtin_amdgcn_rcpf(1.f + __expf(-g0)), v1 = a1 * __builtin_amdgcn_rcpf(1.f + __expf(-g1));
;                 if (e < 2) { u0[2 * e] = v0; u0[2 * e + 1] = v1; } else { u1[2 * e - 4] = v0; u1[2 * e - 3] = v1; } } }
;         *(LAS f32x4*)(U + r * 512 + cc * 8) = u0; *(LAS f32x4*)(U + r * 512 + cc * 8 + 4) = u1; }
;     ...
;     for (int i = 0; i < 4; ++i) { const int tt = wave * 4 + i;
;         const f32x4 a = *(const LAS f32x4*)(U + tt * 512 + lane * 8), b = *(const LAS f32x4*)(U + tt * 512 + lane * 8 + 4);
;         const float mu = wave_sum((a[0] + a[1]) + (a[2] + a[3]) + (b[0] + b[1]) + (b[2] + b[3])) * (1.f / 512.f);
;         const f32x4 da = a - mu, db = b - mu;
;         const float var = wave_sum((da[0] * da[0] + da[1] * da[1]) + (da[2] * da[2] + da[3] * da[3]) + (db[0] * db[0] + db[1] * db[1]) + (db[2] * db[2] + db[3] * db[3])) * (1.f / 512.f);
;         const float rstd = rsqrtf(var + EPS);
;         const f32x4 wa = *(const f32x4*)(ln_w + lane * 8), wb = *(const f32x4*)(ln_w + lane * 8 + 4), ba = *(const f32x4*)(ln_b + lane * 8), bb = *(const f32x4*)(ln_b + lane * 8 + 4);
;         f32x4 ya = da * rstd * wa + ba, yb = db * rstd * wb + bb;
; #pragma unroll
;         for (int e = 0; e < 4; ++e) { ya[e] = ya[e] * __builtin_amdgcn_rcpf(1.f + __expf(-ya[e])); yb[e] = yb[e] * __builtin_amdgcn_rcpf(1.f + __expf(-yb[e])); }
;         u32x4 o; o.x = pk2(ya[0], ya[1]); o.y = pk2(ya[2], ya[3]); o.z = pk2(yb[0], yb[1]); o.w = pk2(yb[2], yb[3]);
;         wt_store16(wsr, MIX + (rowb + t0 + tt) * D + 512 + lane * 8, o); }
;     __syncthreads();
	v_add_f32_e32 v84, v84, v86
	v_fmamk_f32 v84, v84, 0x3b000000, v213
	v_mul_f32_e32 v86, 0x4b800000, v84
	v_cmp_gt_f32_e32 vcc, s27, v84
	s_nop 1
	v_cndmask_b32_e32 v84, v84, v86, vcc
	v_rsq_f32_e32 v84, v84
	s_nop 0
	v_mul_f32_e32 v86, 0x45800000, v84
	v_cndmask_b32_e32 v84, v84, v86, vcc
	v_pk_mul_f32 v[0:1], v[0:1], v[84:85] op_sel_hi:[1,0]
	v_pk_mul_f32 v[4:5], v[4:5], v[84:85] op_sel_hi:[1,0]
	s_waitcnt vmcnt(2)
	v_pk_fma_f32 v[0:1], v[146:147], v[0:1], v[142:143]
	v_pk_mul_f32 v[2:3], v[2:3], v[84:85] op_sel_hi:[1,0]
	v_pk_mul_f32 v[6:7], v[6:7], v[84:85] op_sel_hi:[1,0]
	s_waitcnt vmcnt(0)
	v_pk_fma_f32 v[4:5], v[150:151], v[4:5], v[154:155]
	v_mul_f32_e32 v84, 0xbfb8aa3b, v0
	v_exp_f32_e32 v84, v84
	v_mul_f32_e32 v86, 0xbfb8aa3b, v4
	v_exp_f32_e32 v86, v86
	v_mul_f32_e32 v88, 0xbfb8aa3b, v5
	v_add_f32_e32 v84, 1.0, v84
	v_rcp_f32_e32 v142, v84
	v_add_f32_e32 v84, 1.0, v86
	v_mul_f32_e32 v86, 0xbfb8aa3b, v1
	v_exp_f32_e32 v86, v86
	v_exp_f32_e32 v88, v88
	v_pk_fma_f32 v[2:3], v[148:149], v[2:3], v[144:145]
	v_rcp_f32_e32 v144, v84
	v_add_f32_e32 v84, 1.0, v86
	v_mul_f32_e32 v86, 0xbfb8aa3b, v2
	v_pk_fma_f32 v[6:7], v[152:153], v[6:7], v[156:157]
	v_exp_f32_e32 v86, v86
	v_rcp_f32_e32 v143, v84
	v_add_f32_e32 v84, 1.0, v88
	v_mul_f32_e32 v88, 0xbfb8aa3b, v6
	v_exp_f32_e32 v88, v88
	v_rcp_f32_e32 v145, v84
	v_add_f32_e32 v84, 1.0, v86
	v_mul_f32_e32 v86, 0xbfb8aa3b, v3
	v_exp_f32_e32 v86, v86
	v_rcp_f32_e32 v146, v84
	v_add_f32_e32 v84, 1.0, v88
	v_mul_f32_e32 v88, 0xbfb8aa3b, v7
	v_exp_f32_e32 v88, v88
	v_rcp_f32_e32 v148, v84
	v_add_f32_e32 v84, 1.0, v86
	v_rcp_f32_e32 v147, v84
	v_add_f32_e32 v84, 1.0, v88
	v_rcp_f32_e32 v149, v84
	v_pk_mul_f32 v[0:1], v[0:1], v[142:143]
	v_pk_mul_f32 v[4:5], v[4:5], v[144:145]
	v_pk_mul_f32 v[2:3], v[2:3], v[146:147]
	v_cvt_pk_bf16_f32 v0, v0, v1
	v_cvt_pk_bf16_f32 v1, v2, v3
	v_cvt_pk_bf16_f32 v2, v4, v5
	v_add_lshl_u32 v4, s3, v32, 11
	v_pk_mul_f32 v[6:7], v[6:7], v[148:149]
	v_add3_u32 v4, s70, v4, v214
	v_cvt_pk_bf16_f32 v3, v6, v7
	v_subrev_u32_e32 v4, s84, v4
	buffer_store_dwordx4 v[0:3], v4, s[88:91], 0 offen offset:1024 sc1
	s_barrier
	s_cbranch_scc0 .LBB0_225
.LBB0_221:
	s_bfe_i32 s8, s28, 0x1001a
	s_lshl_b32 s3, s28, 5
	s_lshr_b32 s8, s8, 19
	s_add_i32 s8, s3, s8
	s_and_b32 s8, s8, 0xffffe000
	s_sub_i32 s3, s3, s8
	s_ashr_i32 s8, s28, 31
	s_lshr_b32 s8, s8, 24
	s_add_i32 s8, s28, s8
	s_ashr_i32 s8, s8, 8
	s_ashr_i32 s9, s8, 31
	s_lshl_b64 s[8:9], s[8:9], 13
	v_add_u32_e32 v84, s3, v75
	s_mov_b64 s[10:11], 0
	v_mov_b32_e32 v86, v211
	v_mov_b32_e32 v88, v210
	s_bitcmp1_b32 s28, 0
	s_cbranch_scc0 .Lcp_full
	v_add_u32_e32 v84, 30, v84
	v_add_u32_e32 v86, 0xf000, v86
	v_mov_b32_e32 v88, 0x77f
	v_lshlrev_b32_e32 v104, 2, v128
	v_add_u32_e32 v106, 0x10000, v104
	ds_read_b32 v150, v106
	ds_read_b32 v151, v106 offset:2048
	ds_read_b32 v152, v106 offset:4096
	ds_read_b32 v153, v106 offset:6144
	ds_read_b32 v154, v106 offset:8192
	ds_read_b32 v155, v106 offset:10240
	ds_read_b32 v156, v106 offset:12288
	ds_read_b32 v157, v106 offset:14336
	ds_read_b32 v158, v106 offset:16384
	ds_read_b32 v159, v106 offset:18432
	ds_read_b32 v160, v106 offset:20480
	ds_read_b32 v161, v106 offset:22528
	ds_read_b32 v162, v106 offset:24576
	ds_read_b32 v163, v106 offset:26624
	ds_read_b32 v164, v106 offset:28672
	ds_read_b32 v165, v106 offset:30720
	ds_read_b32 v166, v106 offset:32768
	ds_read_b32 v167, v106 offset:34816
	ds_read_b32 v168, v106 offset:36864
	ds_read_b32 v169, v106 offset:38912
	ds_read_b32 v170, v106 offset:40960
	ds_read_b32 v171, v106 offset:43008
	ds_read_b32 v172, v106 offset:45056
	ds_read_b32 v173, v106 offset:47104
	ds_read_b32 v174, v106 offset:49152
	ds_read_b32 v175, v106 offset:51200
	ds_read_b32 v176, v106 offset:53248
	ds_read_b32 v177, v106 offset:55296
	ds_read_b32 v178, v106 offset:57344
	ds_read_b32 v179, v106 offset:59392
	s_waitcnt lgkmcnt(0)
	ds_write_b32 v104, v150
	ds_write_b32 v104, v151 offset:2048
	ds_write_b32 v104, v152 offset:4096
	ds_write_b32 v104, v153 offset:6144
	ds_write_b32 v104, v154 offset:8192
	ds_write_b32 v104, v155 offset:10240
	ds_write_b32 v104, v156 offset:12288
	ds_write_b32 v104, v157 offset:14336
	ds_write_b32 v104, v158 offset:16384
	ds_write_b32 v104, v159 offset:18432
	ds_write_b32 v104, v160 offset:20480
	ds_write_b32 v104, v161 offset:22528
	ds_write_b32 v104, v162 offset:24576
	ds_write_b32 v104, v163 offset:26624
	ds_write_b32 v104, v164 offset:28672
	ds_write_b32 v104, v165 offset:30720
	ds_write_b32 v104, v166 offset:32768
	ds_write_b32 v104, v167 offset:34816
	ds_write_b32 v104, v168 offset:36864
	ds_write_b32 v104, v169 offset:38912
	ds_write_b32 v104, v170 offset:40960
	ds_write_b32 v104, v171 offset:43008
	ds_write_b32 v104, v172 offset:45056
	ds_write_b32 v104, v173 offset:47104
	ds_write_b32 v104, v174 offset:49152
	ds_write_b32 v104, v175 offset:51200
	ds_write_b32 v104, v176 offset:53248
	ds_write_b32 v104, v177 offset:55296
	ds_write_b32 v104, v178 offset:57344
	ds_write_b32 v104, v179 offset:59392
	s_waitcnt lgkmcnt(0)
	s_barrier
.Lcp_full:
	s_branch .LBB0_223
.LBB0_222:
	s_or_b64 exec, exec, s[14:15]
	v_add_u32_e32 v88, 0x200, v88
	v_cmp_lt_u32_e32 vcc, s26, v88
	ds_write_b128 v86, v[4:7]
	ds_write_b128 v86, v[0:3] offset:16
	v_add_u32_e32 v86, 0x4000, v86
	s_or_b64 s[10:11], vcc, s[10:11]
	v_add_u32_e32 v84, 8, v84
	s_andn2_b64 exec, exec, s[10:11]
	s_cbranch_execz .LBB0_220
